# unit boundary: lead half skips the join barrier and trail half skips its last post-MFMA barrier, so the lead's epilogue overlaps the trail's last MFMA burst (8 main GEMM loops); on top of v62
# baseline (speedup 1.0000x reference)
; #define PG8_STAGEX(rs, bufoff, soff, voff) do { _Pragma("unroll") for (int _i = 0; _i < 2; ++_i) \
;         __builtin_amdgcn_raw_ptr_buffer_load_lds(rs, (LAS unsigned*)(lds + (bufoff) + ldsw + _i * 8192), 16, (voff)[_i], (soff), 0, 0); } while (0)
; #define PG8_LDA(dst, b, h) do { _Pragma("unroll") for (int m = 0; m < 4; ++m) _Pragma("unroll") for (int k = 0; k < 2; ++k) dst[m][k] = *(const LAS bf16x8*)(lds + PG8_SA(b, h) + aoff + m * 2048 + k * 1024); } while (0)
; #define PG8_LDB(dst, b, h) do { _Pragma("unroll") for (int n = 0; n < 2; ++n) _Pragma("unroll") for (int k = 0; k < 2; ++k) dst[n][k] = *(const LAS bf16x8*)(lds + PG8_SB(b, h) + boff + n * 2048 + k * 1024); } while (0)
; #define PG8_WAIT_V(n) asm volatile("s_waitcnt vmcnt(" #n ")" ::: "memory")
; #define PG8_WAIT_L(n) asm volatile("s_waitcnt lgkmcnt(" #n ")" ::: "memory")
; #define PG8_BAR __builtin_amdgcn_s_barrier()
; #define PG8_SCHED __builtin_amdgcn_sched_barrier(0)
;     ...
;             PG8_LDB(B0, 0, 0); PG8_LDB(B1, 0, 1); PG8_SCHED; PG8_LDA(At, 0, 0); PG8_STAGEX(rsA, PG8_SA(1, 1), a1 + hstepA, voffA);
;             PG8_WAIT_V(8); PG8_WAIT_L(0); PG8_BAR; PG8_MMA(0, 0, At, B0); PG8_MMA(0, 1, At, B1); PG8_BAR; PG8_SCHED;
;             PG8_LDA(At, 0, 1); PG8_STAGEX(rsB, PG8_SB(0, 0), b2, voffB); PG8_STAGEX(rsB, PG8_SB(0, 1), b2 + hstepB, voffB); PG8_STAGEX(rsA, PG8_SA(0, 0), a2, voffA);
;             PG8_WAIT_V(8); PG8_WAIT_L(0); PG8_BAR; PG8_MMA(1, 0, At, B0); PG8_MMA(1, 1, At, B1); PG8_BAR; PG8_SCHED;
.LBB0_223:
	v_add_u32_e32 v102, 0x10000, v172
	v_add_u32_e32 v146, 0x14000, v172
	ds_read_b128 v[82:85], v102
	ds_read_b128 v[86:89], v102 offset:1024
	ds_read_b128 v[98:101], v102 offset:2048
	ds_read_b128 v[102:105], v102 offset:3072
	ds_read_b128 v[150:153], v146
	ds_read_b128 v[154:157], v146 offset:1024
	ds_read_b128 v[182:185], v146 offset:2048
	ds_read_b128 v[186:189], v146 offset:3072
	s_add_i32 s42, s50, 0xfff80080
	s_cmp_eq_u32 s52, 28
	s_cselect_b32 s55, s30, s42
	s_cselect_b32 s54, s31, s51
	s_or_b32 s53, s55, 0x80
	s_mov_b32 m0, s22
	ds_read_b128 v[190:193], v173
	ds_read_b128 v[194:197], v173 offset:1024
	ds_read_b128 v[198:201], v173 offset:2048
	ds_read_b128 v[202:205], v173 offset:3072
	ds_read_b128 v[206:209], v173 offset:4096
	ds_read_b128 v[210:213], v173 offset:5120
	ds_read_b128 v[214:217], v173 offset:6144
	ds_read_b128 v[218:221], v173 offset:7168
	buffer_load_dwordx4 v159, s[76:79], s50 offen lds
	s_mov_b32 m0, s23
	s_nop 0
	buffer_load_dwordx4 v163, s[76:79], s50 offen lds
	s_waitcnt vmcnt(8)
	s_waitcnt lgkmcnt(0)
	s_setprio 1
	s_barrier
	v_mfma_f32_16x16x32_bf16 v[142:145], v[82:85], v[190:193], v[142:145]
	v_mfma_f32_16x16x32_bf16 v[142:145], v[86:89], v[194:197], v[142:145]
	v_mfma_f32_16x16x32_bf16 v[134:137], v[98:101], v[190:193], v[134:137]
	v_mfma_f32_16x16x32_bf16 v[134:137], v[102:105], v[194:197], v[134:137]
	v_mfma_f32_16x16x32_bf16 v[118:121], v[98:101], v[198:201], v[118:121]
	v_mfma_f32_16x16x32_bf16 v[118:121], v[102:105], v[202:205], v[118:121]
	v_mfma_f32_16x16x32_bf16 v[126:129], v[82:85], v[198:201], v[126:129]
	v_mfma_f32_16x16x32_bf16 v[126:129], v[86:89], v[202:205], v[126:129]
	v_mfma_f32_16x16x32_bf16 v[110:113], v[82:85], v[206:209], v[110:113]
	v_mfma_f32_16x16x32_bf16 v[110:113], v[86:89], v[210:213], v[110:113]
	v_mfma_f32_16x16x32_bf16 v[94:97], v[98:101], v[206:209], v[94:97]
	v_mfma_f32_16x16x32_bf16 v[94:97], v[102:105], v[210:213], v[94:97]
	v_mfma_f32_16x16x32_bf16 v[70:73], v[98:101], v[214:217], v[70:73]
	v_mfma_f32_16x16x32_bf16 v[70:73], v[102:105], v[218:221], v[70:73]
	v_mfma_f32_16x16x32_bf16 v[78:81], v[82:85], v[214:217], v[78:81]
	v_mfma_f32_16x16x32_bf16 v[78:81], v[86:89], v[218:221], v[78:81]
	v_mfma_f32_16x16x32_bf16 v[138:141], v[150:153], v[190:193], v[138:141]
	v_mfma_f32_16x16x32_bf16 v[138:141], v[154:157], v[194:197], v[138:141]
	v_mfma_f32_16x16x32_bf16 v[130:133], v[182:185], v[190:193], v[130:133]
	v_mfma_f32_16x16x32_bf16 v[130:133], v[186:189], v[194:197], v[130:133]
	v_mfma_f32_16x16x32_bf16 v[114:117], v[182:185], v[198:201], v[114:117]
	v_mfma_f32_16x16x32_bf16 v[114:117], v[186:189], v[202:205], v[114:117]
	v_mfma_f32_16x16x32_bf16 v[122:125], v[150:153], v[198:201], v[122:125]
	v_mfma_f32_16x16x32_bf16 v[122:125], v[154:157], v[202:205], v[122:125]
	v_mfma_f32_16x16x32_bf16 v[106:109], v[150:153], v[206:209], v[106:109]
	v_mfma_f32_16x16x32_bf16 v[106:109], v[154:157], v[210:213], v[106:109]
	v_mfma_f32_16x16x32_bf16 v[90:93], v[182:185], v[206:209], v[90:93]
	v_mfma_f32_16x16x32_bf16 v[90:93], v[186:189], v[210:213], v[90:93]
	v_mfma_f32_16x16x32_bf16 v[66:69], v[182:185], v[214:217], v[66:69]
	v_mfma_f32_16x16x32_bf16 v[66:69], v[186:189], v[218:221], v[66:69]
	v_mfma_f32_16x16x32_bf16 v[74:77], v[150:153], v[214:217], v[74:77]
	v_mfma_f32_16x16x32_bf16 v[74:77], v[154:157], v[218:221], v[74:77]
	s_barrier
	s_setprio 0
	s_mov_b32 m0, s9
	s_mov_b32 s42, s78
	s_mov_b32 s43, s79
	ds_read_b128 v[190:193], v173 offset:16384
	ds_read_b128 v[194:197], v173 offset:17408
	ds_read_b128 v[198:201], v173 offset:18432
	ds_read_b128 v[202:205], v173 offset:19456
	ds_read_b128 v[206:209], v173 offset:20480
	ds_read_b128 v[210:213], v173 offset:21504
	ds_read_b128 v[214:217], v173 offset:22528
	ds_read_b128 v[218:221], v173 offset:23552
	buffer_load_dwordx4 v161, s[40:43], s54 offen lds
	s_mov_b32 m0, s10
	s_add_i32 s56, s54, 0x80000
	buffer_load_dwordx4 v165, s[40:43], s54 offen lds
	s_mov_b32 m0, s11
	s_nop 0
	buffer_load_dwordx4 v161, s[40:43], s56 offen lds
	s_mov_b32 m0, s12
	s_nop 0
	buffer_load_dwordx4 v165, s[40:43], s56 offen lds
	s_mov_b32 m0, s8
	s_nop 0
	buffer_load_dwordx4 v159, s[76:79], s55 offen lds
	s_mov_b32 m0, s13
	s_nop 0
	buffer_load_dwordx4 v163, s[76:79], s55 offen lds
	s_waitcnt vmcnt(8)
	s_waitcnt lgkmcnt(0)
	s_setprio 1
	s_barrier
	v_mfma_f32_16x16x32_bf16 v[62:65], v[82:85], v[190:193], v[62:65]
	v_mfma_f32_16x16x32_bf16 v[62:65], v[86:89], v[194:197], v[62:65]
	v_mfma_f32_16x16x32_bf16 v[54:57], v[98:101], v[190:193], v[54:57]
	v_mfma_f32_16x16x32_bf16 v[54:57], v[102:105], v[194:197], v[54:57]
	v_mfma_f32_16x16x32_bf16 v[38:41], v[98:101], v[198:201], v[38:41]
	v_mfma_f32_16x16x32_bf16 v[38:41], v[102:105], v[202:205], v[38:41]
	v_mfma_f32_16x16x32_bf16 v[46:49], v[82:85], v[198:201], v[46:49]
	v_mfma_f32_16x16x32_bf16 v[46:49], v[86:89], v[202:205], v[46:49]
	v_mfma_f32_16x16x32_bf16 v[30:33], v[82:85], v[206:209], v[30:33]
	v_mfma_f32_16x16x32_bf16 v[30:33], v[86:89], v[210:213], v[30:33]
	v_mfma_f32_16x16x32_bf16 v[22:25], v[98:101], v[206:209], v[22:25]
	v_mfma_f32_16x16x32_bf16 v[22:25], v[102:105], v[210:213], v[22:25]
	v_mfma_f32_16x16x32_bf16 v[6:9], v[98:101], v[214:217], v[6:9]
	v_mfma_f32_16x16x32_bf16 v[6:9], v[102:105], v[218:221], v[6:9]
	v_mfma_f32_16x16x32_bf16 v[14:17], v[82:85], v[214:217], v[14:17]
	v_mfma_f32_16x16x32_bf16 v[14:17], v[86:89], v[218:221], v[14:17]
	v_mfma_f32_16x16x32_bf16 v[58:61], v[150:153], v[190:193], v[58:61]
	v_mfma_f32_16x16x32_bf16 v[58:61], v[154:157], v[194:197], v[58:61]
	v_mfma_f32_16x16x32_bf16 v[50:53], v[182:185], v[190:193], v[50:53]
	v_mfma_f32_16x16x32_bf16 v[50:53], v[186:189], v[194:197], v[50:53]
	v_mfma_f32_16x16x32_bf16 v[34:37], v[182:185], v[198:201], v[34:37]
	v_mfma_f32_16x16x32_bf16 v[34:37], v[186:189], v[202:205], v[34:37]
	v_mfma_f32_16x16x32_bf16 v[42:45], v[150:153], v[198:201], v[42:45]
	v_mfma_f32_16x16x32_bf16 v[42:45], v[154:157], v[202:205], v[42:45]
	v_mfma_f32_16x16x32_bf16 v[26:29], v[150:153], v[206:209], v[26:29]
	v_mfma_f32_16x16x32_bf16 v[26:29], v[154:157], v[210:213], v[26:29]
	v_mfma_f32_16x16x32_bf16 v[18:21], v[182:185], v[206:209], v[18:21]
	v_mfma_f32_16x16x32_bf16 v[18:21], v[186:189], v[210:213], v[18:21]
	v_mfma_f32_16x16x32_bf16 v[2:5], v[182:185], v[214:217], v[2:5]
	v_mfma_f32_16x16x32_bf16 v[2:5], v[186:189], v[218:221], v[2:5]
	v_mfma_f32_16x16x32_bf16 v[10:13], v[150:153], v[214:217], v[10:13]
	v_mfma_f32_16x16x32_bf16 v[10:13], v[154:157], v[218:221], v[10:13]
	s_barrier
; #define PG8_STAGEX(rs, bufoff, soff, voff) do { _Pragma("unroll") for (int _i = 0; _i < 2; ++_i) \
;         __builtin_amdgcn_raw_ptr_buffer_load_lds(rs, (LAS unsigned*)(lds + (bufoff) + ldsw + _i * 8192), 16, (voff)[_i], (soff), 0, 0); } while (0)
; #define PG8_LDA(dst, b, h) do { _Pragma("unroll") for (int m = 0; m < 4; ++m) _Pragma("unroll") for (int k = 0; k < 2; ++k) dst[m][k] = *(const LAS bf16x8*)(lds + PG8_SA(b, h) + aoff + m * 2048 + k * 1024); } while (0)
; #define PG8_LDB(dst, b, h) do { _Pragma("unroll") for (int n = 0; n < 2; ++n) _Pragma("unroll") for (int k = 0; k < 2; ++k) dst[n][k] = *(const LAS bf16x8*)(lds + PG8_SB(b, h) + boff + n * 2048 + k * 1024); } while (0)
; #define PG8_WAIT_V(n) asm volatile("s_waitcnt vmcnt(" #n ")" ::: "memory")
; #define PG8_WAIT_L(n) asm volatile("s_waitcnt lgkmcnt(" #n ")" ::: "memory")
; #define PG8_BAR __builtin_amdgcn_s_barrier()
; #define PG8_SCHED __builtin_amdgcn_sched_barrier(0)
;     ...
;             PG8_LDB(B0, 1, 0); PG8_LDB(B1, 1, 1); PG8_SCHED; PG8_LDA(At, 1, 0); PG8_STAGEX(rsA, PG8_SA(0, 1), a2 + hstepA, voffA);
;             PG8_WAIT_V(8); PG8_WAIT_L(0); PG8_BAR; PG8_MMA(0, 0, At, B0); PG8_MMA(0, 1, At, B1); PG8_BAR; PG8_SCHED;
;             PG8_LDA(At, 1, 1); PG8_STAGEX(rsB, PG8_SB(1, 0), b3, voffB); PG8_STAGEX(rsB, PG8_SB(1, 1), b3 + hstepB, voffB); PG8_STAGEX(rsA, PG8_SA(1, 0), a3, voffA);
;             PG8_WAIT_V(8); PG8_WAIT_L(0); PG8_BAR; PG8_MMA(1, 0, At, B0); PG8_MMA(1, 1, At, B1); PG8_BAR; PG8_SCHED;
;     ...
;         if (wr == 0) PG8_BAR;
	s_setprio 0
	v_add_u32_e32 v102, 0x18000, v172
	v_add_u32_e32 v146, 0x1c000, v172
	ds_read_b128 v[82:85], v102
	ds_read_b128 v[86:89], v102 offset:1024
	ds_read_b128 v[98:101], v102 offset:2048
	ds_read_b128 v[102:105], v102 offset:3072
	ds_read_b128 v[150:153], v146
	ds_read_b128 v[154:157], v146 offset:1024
	ds_read_b128 v[182:185], v146 offset:2048
	ds_read_b128 v[186:189], v146 offset:3072
	s_add_i32 s55, s55, 0x80000
	s_mov_b32 m0, s14
	ds_read_b128 v[190:193], v173 offset:32768
	ds_read_b128 v[194:197], v173 offset:33792
	ds_read_b128 v[198:201], v173 offset:34816
	ds_read_b128 v[202:205], v173 offset:35840
	ds_read_b128 v[206:209], v173 offset:36864
	ds_read_b128 v[210:213], v173 offset:37888
	ds_read_b128 v[214:217], v173 offset:38912
	ds_read_b128 v[218:221], v173 offset:39936
	buffer_load_dwordx4 v159, s[76:79], s55 offen lds
	s_mov_b32 m0, s15
	s_nop 0
	buffer_load_dwordx4 v163, s[76:79], s55 offen lds
	s_waitcnt vmcnt(8)
	s_waitcnt lgkmcnt(0)
	s_setprio 1
	s_barrier
	v_mfma_f32_16x16x32_bf16 v[142:145], v[82:85], v[190:193], v[142:145]
	v_mfma_f32_16x16x32_bf16 v[142:145], v[86:89], v[194:197], v[142:145]
	v_mfma_f32_16x16x32_bf16 v[134:137], v[98:101], v[190:193], v[134:137]
	v_mfma_f32_16x16x32_bf16 v[134:137], v[102:105], v[194:197], v[134:137]
	v_mfma_f32_16x16x32_bf16 v[118:121], v[98:101], v[198:201], v[118:121]
	v_mfma_f32_16x16x32_bf16 v[118:121], v[102:105], v[202:205], v[118:121]
	v_mfma_f32_16x16x32_bf16 v[126:129], v[82:85], v[198:201], v[126:129]
	v_mfma_f32_16x16x32_bf16 v[126:129], v[86:89], v[202:205], v[126:129]
	v_mfma_f32_16x16x32_bf16 v[110:113], v[82:85], v[206:209], v[110:113]
	v_mfma_f32_16x16x32_bf16 v[110:113], v[86:89], v[210:213], v[110:113]
	v_mfma_f32_16x16x32_bf16 v[94:97], v[98:101], v[206:209], v[94:97]
	v_mfma_f32_16x16x32_bf16 v[94:97], v[102:105], v[210:213], v[94:97]
	v_mfma_f32_16x16x32_bf16 v[70:73], v[98:101], v[214:217], v[70:73]
	v_mfma_f32_16x16x32_bf16 v[70:73], v[102:105], v[218:221], v[70:73]
	v_mfma_f32_16x16x32_bf16 v[78:81], v[82:85], v[214:217], v[78:81]
	v_mfma_f32_16x16x32_bf16 v[78:81], v[86:89], v[218:221], v[78:81]
	v_mfma_f32_16x16x32_bf16 v[138:141], v[150:153], v[190:193], v[138:141]
	v_mfma_f32_16x16x32_bf16 v[138:141], v[154:157], v[194:197], v[138:141]
	v_mfma_f32_16x16x32_bf16 v[130:133], v[182:185], v[190:193], v[130:133]
	v_mfma_f32_16x16x32_bf16 v[130:133], v[186:189], v[194:197], v[130:133]
	v_mfma_f32_16x16x32_bf16 v[114:117], v[182:185], v[198:201], v[114:117]
	v_mfma_f32_16x16x32_bf16 v[114:117], v[186:189], v[202:205], v[114:117]
	v_mfma_f32_16x16x32_bf16 v[122:125], v[150:153], v[198:201], v[122:125]
	v_mfma_f32_16x16x32_bf16 v[122:125], v[154:157], v[202:205], v[122:125]
	v_mfma_f32_16x16x32_bf16 v[106:109], v[150:153], v[206:209], v[106:109]
	v_mfma_f32_16x16x32_bf16 v[106:109], v[154:157], v[210:213], v[106:109]
	v_mfma_f32_16x16x32_bf16 v[90:93], v[182:185], v[206:209], v[90:93]
	v_mfma_f32_16x16x32_bf16 v[90:93], v[186:189], v[210:213], v[90:93]
	v_mfma_f32_16x16x32_bf16 v[66:69], v[182:185], v[214:217], v[66:69]
	v_mfma_f32_16x16x32_bf16 v[66:69], v[186:189], v[218:221], v[66:69]
	v_mfma_f32_16x16x32_bf16 v[74:77], v[150:153], v[214:217], v[74:77]
	v_mfma_f32_16x16x32_bf16 v[74:77], v[154:157], v[218:221], v[74:77]
	s_barrier
	s_setprio 0
	s_mov_b32 m0, s16
	s_or_b32 s55, s54, 0x80
	ds_read_b128 v[190:193], v173 offset:49152
	ds_read_b128 v[194:197], v173 offset:50176
	ds_read_b128 v[198:201], v173 offset:51200
	ds_read_b128 v[202:205], v173 offset:52224
	ds_read_b128 v[206:209], v173 offset:53248
	ds_read_b128 v[210:213], v173 offset:54272
	ds_read_b128 v[214:217], v173 offset:55296
	ds_read_b128 v[218:221], v173 offset:56320
	buffer_load_dwordx4 v161, s[40:43], s55 offen lds
	s_mov_b32 m0, s17
	s_add_i32 s54, s54, 0x80080
	buffer_load_dwordx4 v165, s[40:43], s55 offen lds
	s_mov_b32 m0, s20
	s_nop 0
	buffer_load_dwordx4 v161, s[40:43], s54 offen lds
	s_mov_b32 m0, s21
	s_nop 0
	buffer_load_dwordx4 v165, s[40:43], s54 offen lds
	s_mov_b32 m0, s18
	s_cmp_eq_u32 s52, 28
	buffer_load_dwordx4 v159, s[76:79], s53 offen lds
	s_mov_b32 m0, s19
	s_cselect_b64 vcc, s[44:45], 0
	buffer_load_dwordx4 v163, s[76:79], s53 offen lds
	s_waitcnt vmcnt(8)
	s_waitcnt lgkmcnt(0)
	s_setprio 1
	s_barrier
	v_mfma_f32_16x16x32_bf16 v[62:65], v[82:85], v[190:193], v[62:65]
	v_mfma_f32_16x16x32_bf16 v[62:65], v[86:89], v[194:197], v[62:65]
	v_mfma_f32_16x16x32_bf16 v[54:57], v[98:101], v[190:193], v[54:57]
	v_mfma_f32_16x16x32_bf16 v[54:57], v[102:105], v[194:197], v[54:57]
	v_mfma_f32_16x16x32_bf16 v[38:41], v[98:101], v[198:201], v[38:41]
	v_mfma_f32_16x16x32_bf16 v[38:41], v[102:105], v[202:205], v[38:41]
	v_mfma_f32_16x16x32_bf16 v[46:49], v[82:85], v[198:201], v[46:49]
	v_mfma_f32_16x16x32_bf16 v[46:49], v[86:89], v[202:205], v[46:49]
	v_mfma_f32_16x16x32_bf16 v[30:33], v[82:85], v[206:209], v[30:33]
	v_mfma_f32_16x16x32_bf16 v[30:33], v[86:89], v[210:213], v[30:33]
	v_mfma_f32_16x16x32_bf16 v[22:25], v[98:101], v[206:209], v[22:25]
	v_mfma_f32_16x16x32_bf16 v[22:25], v[102:105], v[210:213], v[22:25]
	v_mfma_f32_16x16x32_bf16 v[6:9], v[98:101], v[214:217], v[6:9]
	v_mfma_f32_16x16x32_bf16 v[6:9], v[102:105], v[218:221], v[6:9]
	v_mfma_f32_16x16x32_bf16 v[14:17], v[82:85], v[214:217], v[14:17]
	v_mfma_f32_16x16x32_bf16 v[14:17], v[86:89], v[218:221], v[14:17]
	v_mfma_f32_16x16x32_bf16 v[58:61], v[150:153], v[190:193], v[58:61]
	v_mfma_f32_16x16x32_bf16 v[58:61], v[154:157], v[194:197], v[58:61]
	v_mfma_f32_16x16x32_bf16 v[50:53], v[182:185], v[190:193], v[50:53]
	v_mfma_f32_16x16x32_bf16 v[50:53], v[186:189], v[194:197], v[50:53]
	v_mfma_f32_16x16x32_bf16 v[34:37], v[182:185], v[198:201], v[34:37]
	v_mfma_f32_16x16x32_bf16 v[34:37], v[186:189], v[202:205], v[34:37]
	v_mfma_f32_16x16x32_bf16 v[42:45], v[150:153], v[198:201], v[42:45]
	v_mfma_f32_16x16x32_bf16 v[42:45], v[154:157], v[202:205], v[42:45]
	v_mfma_f32_16x16x32_bf16 v[26:29], v[150:153], v[206:209], v[26:29]
	v_mfma_f32_16x16x32_bf16 v[26:29], v[154:157], v[210:213], v[26:29]
	v_mfma_f32_16x16x32_bf16 v[18:21], v[182:185], v[206:209], v[18:21]
	v_mfma_f32_16x16x32_bf16 v[18:21], v[186:189], v[210:213], v[18:21]
	v_mfma_f32_16x16x32_bf16 v[2:5], v[182:185], v[214:217], v[2:5]
	v_mfma_f32_16x16x32_bf16 v[2:5], v[186:189], v[218:221], v[2:5]
	v_mfma_f32_16x16x32_bf16 v[10:13], v[150:153], v[214:217], v[10:13]
	v_mfma_f32_16x16x32_bf16 v[10:13], v[154:157], v[218:221], v[10:13]
	s_cbranch_vccnz .Lee_skip_223
	s_barrier
.Lee_skip_223:
	s_setprio 0
	s_add_i32 s52, s52, 2
	s_addk_i32 s50, 0x100
	s_addk_i32 s51, 0x100
	s_cmp_gt_u32 s52, 29
	s_cbranch_scc0 .LBB0_223

; #define PG8_STAGEX(rs, bufoff, soff, voff) do { _Pragma("unroll") for (int _i = 0; _i < 2; ++_i) \
;         __builtin_amdgcn_raw_ptr_buffer_load_lds(rs, (LAS unsigned*)(lds + (bufoff) + ldsw + _i * 8192), 16, (voff)[_i], (soff), 0, 0); } while (0)
; #define PG8_LDA(dst, b, h) do { _Pragma("unroll") for (int m = 0; m < 4; ++m) _Pragma("unroll") for (int k = 0; k < 2; ++k) dst[m][k] = *(const LAS bf16x8*)(lds + PG8_SA(b, h) + aoff + m * 2048 + k * 1024); } while (0)
; #define PG8_LDB(dst, b, h) do { _Pragma("unroll") for (int n = 0; n < 2; ++n) _Pragma("unroll") for (int k = 0; k < 2; ++k) dst[n][k] = *(const LAS bf16x8*)(lds + PG8_SB(b, h) + boff + n * 2048 + k * 1024); } while (0)
; #define PG8_WAIT_V(n) asm volatile("s_waitcnt vmcnt(" #n ")" ::: "memory")
; #define PG8_WAIT_L(n) asm volatile("s_waitcnt lgkmcnt(" #n ")" ::: "memory")
; #define PG8_BAR __builtin_amdgcn_s_barrier()
; #define PG8_SCHED __builtin_amdgcn_sched_barrier(0)
;     ...
;             PG8_LDB(B0, 0, 0); PG8_LDB(B1, 0, 1); PG8_SCHED; PG8_LDA(At, 0, 0); PG8_STAGEX(rsA, PG8_SA(1, 1), a1 + hstepA, voffA);
;             PG8_WAIT_V(8); PG8_WAIT_L(0); PG8_BAR; PG8_MMA(0, 0, At, B0); PG8_MMA(0, 1, At, B1); PG8_BAR; PG8_SCHED;
;             PG8_LDA(At, 0, 1); PG8_STAGEX(rsB, PG8_SB(0, 0), b2, voffB); PG8_STAGEX(rsB, PG8_SB(0, 1), b2 + hstepB, voffB); PG8_STAGEX(rsA, PG8_SA(0, 0), a2, voffA);
;             PG8_WAIT_V(8); PG8_WAIT_L(0); PG8_BAR; PG8_MMA(1, 0, At, B0); PG8_MMA(1, 1, At, B1); PG8_BAR; PG8_SCHED;
.LBB0_323:
	v_add_u32_e32 v118, 0x10000, v210
	v_add_u32_e32 v160, 0x14000, v210
	ds_read_b128 v[106:109], v118
	ds_read_b128 v[110:113], v118 offset:1024
	ds_read_b128 v[114:117], v118 offset:2048
	ds_read_b128 v[118:121], v118 offset:3072
	ds_read_b128 v[122:125], v160
	ds_read_b128 v[134:137], v160 offset:1024
	ds_read_b128 v[156:159], v160 offset:2048
	ds_read_b128 v[160:163], v160 offset:3072
	s_add_i32 s42, s51, 0xffea8080
	s_cmpk_eq_i32 s58, 0x52
	s_cselect_b32 s61, s30, s42
	s_cselect_b32 s60, s31, s57
	s_or_b32 s59, s61, 0x80
	s_mov_b32 m0, s68
	ds_read_b128 v[164:167], v211
	ds_read_b128 v[168:171], v211 offset:1024
	ds_read_b128 v[182:185], v211 offset:2048
	ds_read_b128 v[186:189], v211 offset:3072
	ds_read_b128 v[190:193], v211 offset:4096
	ds_read_b128 v[194:197], v211 offset:5120
	ds_read_b128 v[198:201], v211 offset:6144
	ds_read_b128 v[202:205], v211 offset:7168
	buffer_load_dwordx4 v178, s[76:79], s51 offen lds
	s_mov_b32 m0, s69
	s_nop 0
	buffer_load_dwordx4 v206, s[76:79], s51 offen lds
	s_waitcnt vmcnt(8)
	s_waitcnt lgkmcnt(0)
	s_setprio 1
	s_barrier
	v_mfma_f32_16x16x32_bf16 v[150:153], v[106:109], v[164:167], v[150:153]
	v_mfma_f32_16x16x32_bf16 v[150:153], v[110:113], v[168:171], v[150:153]
	v_mfma_f32_16x16x32_bf16 v[146:149], v[114:117], v[164:167], v[146:149]
	v_mfma_f32_16x16x32_bf16 v[146:149], v[118:121], v[168:171], v[146:149]
	v_mfma_f32_16x16x32_bf16 v[138:141], v[114:117], v[182:185], v[138:141]
	v_mfma_f32_16x16x32_bf16 v[138:141], v[118:121], v[186:189], v[138:141]
	v_mfma_f32_16x16x32_bf16 v[142:145], v[106:109], v[182:185], v[142:145]
	v_mfma_f32_16x16x32_bf16 v[142:145], v[110:113], v[186:189], v[142:145]
	v_mfma_f32_16x16x32_bf16 v[130:133], v[106:109], v[190:193], v[130:133]
	v_mfma_f32_16x16x32_bf16 v[130:133], v[110:113], v[194:197], v[130:133]
	v_mfma_f32_16x16x32_bf16 v[126:129], v[114:117], v[190:193], v[126:129]
	v_mfma_f32_16x16x32_bf16 v[126:129], v[118:121], v[194:197], v[126:129]
	v_mfma_f32_16x16x32_bf16 v[98:101], v[114:117], v[198:201], v[98:101]
	v_mfma_f32_16x16x32_bf16 v[98:101], v[118:121], v[202:205], v[98:101]
	v_mfma_f32_16x16x32_bf16 v[102:105], v[106:109], v[198:201], v[102:105]
	v_mfma_f32_16x16x32_bf16 v[102:105], v[110:113], v[202:205], v[102:105]
	v_mfma_f32_16x16x32_bf16 v[62:65], v[122:125], v[164:167], v[62:65]
	v_mfma_f32_16x16x32_bf16 v[62:65], v[134:137], v[168:171], v[62:65]
	v_mfma_f32_16x16x32_bf16 v[58:61], v[156:159], v[164:167], v[58:61]
	v_mfma_f32_16x16x32_bf16 v[58:61], v[160:163], v[168:171], v[58:61]
	v_mfma_f32_16x16x32_bf16 v[50:53], v[156:159], v[182:185], v[50:53]
	v_mfma_f32_16x16x32_bf16 v[50:53], v[160:163], v[186:189], v[50:53]
	v_mfma_f32_16x16x32_bf16 v[54:57], v[122:125], v[182:185], v[54:57]
	v_mfma_f32_16x16x32_bf16 v[54:57], v[134:137], v[186:189], v[54:57]
	v_mfma_f32_16x16x32_bf16 v[46:49], v[122:125], v[190:193], v[46:49]
	v_mfma_f32_16x16x32_bf16 v[46:49], v[134:137], v[194:197], v[46:49]
	v_mfma_f32_16x16x32_bf16 v[42:45], v[156:159], v[190:193], v[42:45]
	v_mfma_f32_16x16x32_bf16 v[42:45], v[160:163], v[194:197], v[42:45]
	v_mfma_f32_16x16x32_bf16 v[34:37], v[156:159], v[198:201], v[34:37]
	v_mfma_f32_16x16x32_bf16 v[34:37], v[160:163], v[202:205], v[34:37]
	v_mfma_f32_16x16x32_bf16 v[38:41], v[122:125], v[198:201], v[38:41]
	v_mfma_f32_16x16x32_bf16 v[38:41], v[134:137], v[202:205], v[38:41]
	s_barrier
	s_setprio 0
	s_mov_b32 m0, s15
	s_mov_b32 s42, s78
	s_mov_b32 s43, s79
	ds_read_b128 v[164:167], v211 offset:16384
	ds_read_b128 v[168:171], v211 offset:17408
	ds_read_b128 v[182:185], v211 offset:18432
	ds_read_b128 v[186:189], v211 offset:19456
	ds_read_b128 v[190:193], v211 offset:20480
	ds_read_b128 v[194:197], v211 offset:21504
	ds_read_b128 v[198:201], v211 offset:22528
	ds_read_b128 v[202:205], v211 offset:23552
	buffer_load_dwordx4 v179, s[40:43], s60 offen lds
	s_mov_b32 m0, s16
	s_add_i32 s62, s60, 0x158000
	buffer_load_dwordx4 v207, s[40:43], s60 offen lds
	s_mov_b32 m0, s17
	s_nop 0
	buffer_load_dwordx4 v179, s[40:43], s62 offen lds
	s_mov_b32 m0, s18
	s_nop 0
	buffer_load_dwordx4 v207, s[40:43], s62 offen lds
	s_mov_b32 m0, s14
	s_nop 0
	buffer_load_dwordx4 v178, s[76:79], s61 offen lds
	s_mov_b32 m0, s19
	s_nop 0
	buffer_load_dwordx4 v206, s[76:79], s61 offen lds
	s_waitcnt vmcnt(8)
	s_waitcnt lgkmcnt(0)
	s_setprio 1
	s_barrier
	v_mfma_f32_16x16x32_bf16 v[94:97], v[106:109], v[164:167], v[94:97]
	v_mfma_f32_16x16x32_bf16 v[94:97], v[110:113], v[168:171], v[94:97]
	v_mfma_f32_16x16x32_bf16 v[90:93], v[114:117], v[164:167], v[90:93]
	v_mfma_f32_16x16x32_bf16 v[90:93], v[118:121], v[168:171], v[90:93]
	v_mfma_f32_16x16x32_bf16 v[82:85], v[114:117], v[182:185], v[82:85]
	v_mfma_f32_16x16x32_bf16 v[82:85], v[118:121], v[186:189], v[82:85]
	v_mfma_f32_16x16x32_bf16 v[86:89], v[106:109], v[182:185], v[86:89]
	v_mfma_f32_16x16x32_bf16 v[86:89], v[110:113], v[186:189], v[86:89]
	v_mfma_f32_16x16x32_bf16 v[78:81], v[106:109], v[190:193], v[78:81]
	v_mfma_f32_16x16x32_bf16 v[78:81], v[110:113], v[194:197], v[78:81]
	v_mfma_f32_16x16x32_bf16 v[74:77], v[114:117], v[190:193], v[74:77]
	v_mfma_f32_16x16x32_bf16 v[74:77], v[118:121], v[194:197], v[74:77]
	v_mfma_f32_16x16x32_bf16 v[66:69], v[114:117], v[198:201], v[66:69]
	v_mfma_f32_16x16x32_bf16 v[66:69], v[118:121], v[202:205], v[66:69]
	v_mfma_f32_16x16x32_bf16 v[70:73], v[106:109], v[198:201], v[70:73]
	v_mfma_f32_16x16x32_bf16 v[70:73], v[110:113], v[202:205], v[70:73]
	v_mfma_f32_16x16x32_bf16 v[30:33], v[122:125], v[164:167], v[30:33]
	v_mfma_f32_16x16x32_bf16 v[30:33], v[134:137], v[168:171], v[30:33]
	v_mfma_f32_16x16x32_bf16 v[26:29], v[156:159], v[164:167], v[26:29]
	v_mfma_f32_16x16x32_bf16 v[26:29], v[160:163], v[168:171], v[26:29]
	v_mfma_f32_16x16x32_bf16 v[18:21], v[156:159], v[182:185], v[18:21]
	v_mfma_f32_16x16x32_bf16 v[18:21], v[160:163], v[186:189], v[18:21]
	v_mfma_f32_16x16x32_bf16 v[22:25], v[122:125], v[182:185], v[22:25]
	v_mfma_f32_16x16x32_bf16 v[22:25], v[134:137], v[186:189], v[22:25]
	v_mfma_f32_16x16x32_bf16 v[14:17], v[122:125], v[190:193], v[14:17]
	v_mfma_f32_16x16x32_bf16 v[14:17], v[134:137], v[194:197], v[14:17]
	v_mfma_f32_16x16x32_bf16 v[10:13], v[156:159], v[190:193], v[10:13]
	v_mfma_f32_16x16x32_bf16 v[10:13], v[160:163], v[194:197], v[10:13]
	v_mfma_f32_16x16x32_bf16 v[2:5], v[156:159], v[198:201], v[2:5]
	v_mfma_f32_16x16x32_bf16 v[2:5], v[160:163], v[202:205], v[2:5]
	v_mfma_f32_16x16x32_bf16 v[6:9], v[122:125], v[198:201], v[6:9]
	v_mfma_f32_16x16x32_bf16 v[6:9], v[134:137], v[202:205], v[6:9]
	s_barrier
; #define PG8_STAGEX(rs, bufoff, soff, voff) do { _Pragma("unroll") for (int _i = 0; _i < 2; ++_i) \
;         __builtin_amdgcn_raw_ptr_buffer_load_lds(rs, (LAS unsigned*)(lds + (bufoff) + ldsw + _i * 8192), 16, (voff)[_i], (soff), 0, 0); } while (0)
; #define PG8_LDA(dst, b, h) do { _Pragma("unroll") for (int m = 0; m < 4; ++m) _Pragma("unroll") for (int k = 0; k < 2; ++k) dst[m][k] = *(const LAS bf16x8*)(lds + PG8_SA(b, h) + aoff + m * 2048 + k * 1024); } while (0)
; #define PG8_LDB(dst, b, h) do { _Pragma("unroll") for (int n = 0; n < 2; ++n) _Pragma("unroll") for (int k = 0; k < 2; ++k) dst[n][k] = *(const LAS bf16x8*)(lds + PG8_SB(b, h) + boff + n * 2048 + k * 1024); } while (0)
; #define PG8_WAIT_V(n) asm volatile("s_waitcnt vmcnt(" #n ")" ::: "memory")
; #define PG8_WAIT_L(n) asm volatile("s_waitcnt lgkmcnt(" #n ")" ::: "memory")
; #define PG8_BAR __builtin_amdgcn_s_barrier()
; #define PG8_SCHED __builtin_amdgcn_sched_barrier(0)
;     ...
;             PG8_LDB(B0, 1, 0); PG8_LDB(B1, 1, 1); PG8_SCHED; PG8_LDA(At, 1, 0); PG8_STAGEX(rsA, PG8_SA(0, 1), a2 + hstepA, voffA);
;             PG8_WAIT_V(8); PG8_WAIT_L(0); PG8_BAR; PG8_MMA(0, 0, At, B0); PG8_MMA(0, 1, At, B1); PG8_BAR; PG8_SCHED;
;             PG8_LDA(At, 1, 1); PG8_STAGEX(rsB, PG8_SB(1, 0), b3, voffB); PG8_STAGEX(rsB, PG8_SB(1, 1), b3 + hstepB, voffB); PG8_STAGEX(rsA, PG8_SA(1, 0), a3, voffA);
;             PG8_WAIT_V(8); PG8_WAIT_L(0); PG8_BAR; PG8_MMA(1, 0, At, B0); PG8_MMA(1, 1, At, B1); PG8_BAR; PG8_SCHED;
;     ...
;         if (wr == 0) PG8_BAR;
	s_setprio 0
	v_add_u32_e32 v118, 0x18000, v210
	v_add_u32_e32 v160, 0x1c000, v210
	ds_read_b128 v[106:109], v118
	ds_read_b128 v[110:113], v118 offset:1024
	ds_read_b128 v[114:117], v118 offset:2048
	ds_read_b128 v[118:121], v118 offset:3072
	ds_read_b128 v[122:125], v160
	ds_read_b128 v[134:137], v160 offset:1024
	ds_read_b128 v[156:159], v160 offset:2048
	ds_read_b128 v[160:163], v160 offset:3072
	s_add_i32 s61, s61, 0x158000
	s_mov_b32 m0, s20
	ds_read_b128 v[164:167], v211 offset:32768
	ds_read_b128 v[168:171], v211 offset:33792
	ds_read_b128 v[182:185], v211 offset:34816
	ds_read_b128 v[186:189], v211 offset:35840
	ds_read_b128 v[190:193], v211 offset:36864
	ds_read_b128 v[194:197], v211 offset:37888
	ds_read_b128 v[198:201], v211 offset:38912
	ds_read_b128 v[202:205], v211 offset:39936
	buffer_load_dwordx4 v178, s[76:79], s61 offen lds
	s_mov_b32 m0, s21
	s_nop 0
	buffer_load_dwordx4 v206, s[76:79], s61 offen lds
	s_waitcnt vmcnt(8)
	s_waitcnt lgkmcnt(0)
	s_setprio 1
	s_barrier
	v_mfma_f32_16x16x32_bf16 v[150:153], v[106:109], v[164:167], v[150:153]
	v_mfma_f32_16x16x32_bf16 v[150:153], v[110:113], v[168:171], v[150:153]
	v_mfma_f32_16x16x32_bf16 v[146:149], v[114:117], v[164:167], v[146:149]
	v_mfma_f32_16x16x32_bf16 v[146:149], v[118:121], v[168:171], v[146:149]
	v_mfma_f32_16x16x32_bf16 v[138:141], v[114:117], v[182:185], v[138:141]
	v_mfma_f32_16x16x32_bf16 v[138:141], v[118:121], v[186:189], v[138:141]
	v_mfma_f32_16x16x32_bf16 v[142:145], v[106:109], v[182:185], v[142:145]
	v_mfma_f32_16x16x32_bf16 v[142:145], v[110:113], v[186:189], v[142:145]
	v_mfma_f32_16x16x32_bf16 v[130:133], v[106:109], v[190:193], v[130:133]
	v_mfma_f32_16x16x32_bf16 v[130:133], v[110:113], v[194:197], v[130:133]
	v_mfma_f32_16x16x32_bf16 v[126:129], v[114:117], v[190:193], v[126:129]
	v_mfma_f32_16x16x32_bf16 v[126:129], v[118:121], v[194:197], v[126:129]
	v_mfma_f32_16x16x32_bf16 v[98:101], v[114:117], v[198:201], v[98:101]
	v_mfma_f32_16x16x32_bf16 v[98:101], v[118:121], v[202:205], v[98:101]
	v_mfma_f32_16x16x32_bf16 v[102:105], v[106:109], v[198:201], v[102:105]
	v_mfma_f32_16x16x32_bf16 v[102:105], v[110:113], v[202:205], v[102:105]
	v_mfma_f32_16x16x32_bf16 v[62:65], v[122:125], v[164:167], v[62:65]
	v_mfma_f32_16x16x32_bf16 v[62:65], v[134:137], v[168:171], v[62:65]
	v_mfma_f32_16x16x32_bf16 v[58:61], v[156:159], v[164:167], v[58:61]
	v_mfma_f32_16x16x32_bf16 v[58:61], v[160:163], v[168:171], v[58:61]
	v_mfma_f32_16x16x32_bf16 v[50:53], v[156:159], v[182:185], v[50:53]
	v_mfma_f32_16x16x32_bf16 v[50:53], v[160:163], v[186:189], v[50:53]
	v_mfma_f32_16x16x32_bf16 v[54:57], v[122:125], v[182:185], v[54:57]
	v_mfma_f32_16x16x32_bf16 v[54:57], v[134:137], v[186:189], v[54:57]
	v_mfma_f32_16x16x32_bf16 v[46:49], v[122:125], v[190:193], v[46:49]
	v_mfma_f32_16x16x32_bf16 v[46:49], v[134:137], v[194:197], v[46:49]
	v_mfma_f32_16x16x32_bf16 v[42:45], v[156:159], v[190:193], v[42:45]
	v_mfma_f32_16x16x32_bf16 v[42:45], v[160:163], v[194:197], v[42:45]
	v_mfma_f32_16x16x32_bf16 v[34:37], v[156:159], v[198:201], v[34:37]
	v_mfma_f32_16x16x32_bf16 v[34:37], v[160:163], v[202:205], v[34:37]
	v_mfma_f32_16x16x32_bf16 v[38:41], v[122:125], v[198:201], v[38:41]
	v_mfma_f32_16x16x32_bf16 v[38:41], v[134:137], v[202:205], v[38:41]
	s_barrier
	s_setprio 0
	s_mov_b32 m0, s28
	s_or_b32 s61, s60, 0x80
	ds_read_b128 v[164:167], v211 offset:49152
	ds_read_b128 v[168:171], v211 offset:50176
	ds_read_b128 v[182:185], v211 offset:51200
	ds_read_b128 v[186:189], v211 offset:52224
	ds_read_b128 v[190:193], v211 offset:53248
	ds_read_b128 v[194:197], v211 offset:54272
	ds_read_b128 v[198:201], v211 offset:55296
	ds_read_b128 v[202:205], v211 offset:56320
	buffer_load_dwordx4 v179, s[40:43], s61 offen lds
	s_mov_b32 m0, s29
	s_add_i32 s60, s60, 0x158080
	buffer_load_dwordx4 v207, s[40:43], s61 offen lds
	s_mov_b32 m0, s66
	s_nop 0
	buffer_load_dwordx4 v179, s[40:43], s60 offen lds
	s_mov_b32 m0, s67
	s_nop 0
	buffer_load_dwordx4 v207, s[40:43], s60 offen lds
	s_mov_b32 m0, s54
	s_cmpk_eq_i32 s58, 0x52
	buffer_load_dwordx4 v178, s[76:79], s59 offen lds
	s_mov_b32 m0, s55
	s_cselect_b64 vcc, s[46:47], 0
	buffer_load_dwordx4 v206, s[76:79], s59 offen lds
	s_waitcnt vmcnt(8)
	s_waitcnt lgkmcnt(0)
	s_setprio 1
	s_barrier
	v_mfma_f32_16x16x32_bf16 v[94:97], v[106:109], v[164:167], v[94:97]
	v_mfma_f32_16x16x32_bf16 v[94:97], v[110:113], v[168:171], v[94:97]
	v_mfma_f32_16x16x32_bf16 v[90:93], v[114:117], v[164:167], v[90:93]
	v_mfma_f32_16x16x32_bf16 v[90:93], v[118:121], v[168:171], v[90:93]
	v_mfma_f32_16x16x32_bf16 v[82:85], v[114:117], v[182:185], v[82:85]
	v_mfma_f32_16x16x32_bf16 v[82:85], v[118:121], v[186:189], v[82:85]
	v_mfma_f32_16x16x32_bf16 v[86:89], v[106:109], v[182:185], v[86:89]
	v_mfma_f32_16x16x32_bf16 v[86:89], v[110:113], v[186:189], v[86:89]
	v_mfma_f32_16x16x32_bf16 v[78:81], v[106:109], v[190:193], v[78:81]
	v_mfma_f32_16x16x32_bf16 v[78:81], v[110:113], v[194:197], v[78:81]
	v_mfma_f32_16x16x32_bf16 v[74:77], v[114:117], v[190:193], v[74:77]
	v_mfma_f32_16x16x32_bf16 v[74:77], v[118:121], v[194:197], v[74:77]
	v_mfma_f32_16x16x32_bf16 v[66:69], v[114:117], v[198:201], v[66:69]
	v_mfma_f32_16x16x32_bf16 v[66:69], v[118:121], v[202:205], v[66:69]
	v_mfma_f32_16x16x32_bf16 v[70:73], v[106:109], v[198:201], v[70:73]
	v_mfma_f32_16x16x32_bf16 v[70:73], v[110:113], v[202:205], v[70:73]
	v_mfma_f32_16x16x32_bf16 v[30:33], v[122:125], v[164:167], v[30:33]
	v_mfma_f32_16x16x32_bf16 v[30:33], v[134:137], v[168:171], v[30:33]
	v_mfma_f32_16x16x32_bf16 v[26:29], v[156:159], v[164:167], v[26:29]
	v_mfma_f32_16x16x32_bf16 v[26:29], v[160:163], v[168:171], v[26:29]
	v_mfma_f32_16x16x32_bf16 v[18:21], v[156:159], v[182:185], v[18:21]
	v_mfma_f32_16x16x32_bf16 v[18:21], v[160:163], v[186:189], v[18:21]
	v_mfma_f32_16x16x32_bf16 v[22:25], v[122:125], v[182:185], v[22:25]
	v_mfma_f32_16x16x32_bf16 v[22:25], v[134:137], v[186:189], v[22:25]
	v_mfma_f32_16x16x32_bf16 v[14:17], v[122:125], v[190:193], v[14:17]
	v_mfma_f32_16x16x32_bf16 v[14:17], v[134:137], v[194:197], v[14:17]
	v_mfma_f32_16x16x32_bf16 v[10:13], v[156:159], v[190:193], v[10:13]
	v_mfma_f32_16x16x32_bf16 v[10:13], v[160:163], v[194:197], v[10:13]
	v_mfma_f32_16x16x32_bf16 v[2:5], v[156:159], v[198:201], v[2:5]
	v_mfma_f32_16x16x32_bf16 v[2:5], v[160:163], v[202:205], v[2:5]
	v_mfma_f32_16x16x32_bf16 v[6:9], v[122:125], v[198:201], v[6:9]
	v_mfma_f32_16x16x32_bf16 v[6:9], v[134:137], v[202:205], v[6:9]
	s_cbranch_vccnz .Lee_skip_323
	s_barrier
.Lee_skip_323:
	s_setprio 0
	s_add_i32 s58, s58, 2
	s_addk_i32 s51, 0x100
	s_addk_i32 s57, 0x100
	s_cmpk_gt_u32 s58, 0x53
	s_cbranch_scc0 .LBB0_323

; #define PG8_STAGEX(rs, bufoff, soff, voff) do { _Pragma("unroll") for (int _i = 0; _i < 2; ++_i) \
;         __builtin_amdgcn_raw_ptr_buffer_load_lds(rs, (LAS unsigned*)(lds + (bufoff) + ldsw + _i * 8192), 16, (voff)[_i], (soff), 0, 0); } while (0)
; #define PG8_LDA(dst, b, h) do { _Pragma("unroll") for (int m = 0; m < 4; ++m) _Pragma("unroll") for (int k = 0; k < 2; ++k) dst[m][k] = *(const LAS bf16x8*)(lds + PG8_SA(b, h) + aoff + m * 2048 + k * 1024); } while (0)
; #define PG8_LDB(dst, b, h) do { _Pragma("unroll") for (int n = 0; n < 2; ++n) _Pragma("unroll") for (int k = 0; k < 2; ++k) dst[n][k] = *(const LAS bf16x8*)(lds + PG8_SB(b, h) + boff + n * 2048 + k * 1024); } while (0)
; #define PG8_WAIT_V(n) asm volatile("s_waitcnt vmcnt(" #n ")" ::: "memory")
; #define PG8_WAIT_L(n) asm volatile("s_waitcnt lgkmcnt(" #n ")" ::: "memory")
; #define PG8_BAR __builtin_amdgcn_s_barrier()
; #define PG8_SCHED __builtin_amdgcn_sched_barrier(0)
;     ...
;             PG8_LDB(B0, 0, 0); PG8_LDB(B1, 0, 1); PG8_SCHED; PG8_LDA(At, 0, 0); PG8_STAGEX(rsA, PG8_SA(1, 1), a1 + hstepA, voffA);
;             PG8_WAIT_V(8); PG8_WAIT_L(0); PG8_BAR; PG8_MMA(0, 0, At, B0); PG8_MMA(0, 1, At, B1); PG8_BAR; PG8_SCHED;
;             PG8_LDA(At, 0, 1); PG8_STAGEX(rsB, PG8_SB(0, 0), b2, voffB); PG8_STAGEX(rsB, PG8_SB(0, 1), b2 + hstepB, voffB); PG8_STAGEX(rsA, PG8_SA(0, 0), a2, voffA);
;             PG8_WAIT_V(8); PG8_WAIT_L(0); PG8_BAR; PG8_MMA(1, 0, At, B0); PG8_MMA(1, 1, At, B1); PG8_BAR; PG8_SCHED;
.LBB0_437:
	v_add_u32_e32 v142, 0x10000, v220
	v_add_u32_e32 v158, 0x14000, v220
	ds_read_b128 v[130:133], v142
	ds_read_b128 v[134:137], v142 offset:1024
	ds_read_b128 v[138:141], v142 offset:2048
	ds_read_b128 v[142:145], v142 offset:3072
	ds_read_b128 v[146:149], v158
	ds_read_b128 v[150:153], v158 offset:1024
	ds_read_b128 v[154:157], v158 offset:2048
	ds_read_b128 v[158:161], v158 offset:3072
	s_add_i32 s30, s7, 0xfff80080
	s_cmp_eq_u32 s29, 28
	s_cselect_b32 s50, s2, s30
	s_cselect_b32 s31, s5, s28
	s_or_b32 s30, s50, 0x80
	s_mov_b32 m0, s20
	ds_read_b128 v[162:165], v221
	ds_read_b128 v[170:173], v221 offset:1024
	ds_read_b128 v[182:185], v221 offset:2048
	ds_read_b128 v[186:189], v221 offset:3072
	ds_read_b128 v[190:193], v221 offset:4096
	ds_read_b128 v[194:197], v221 offset:5120
	ds_read_b128 v[198:201], v221 offset:6144
	ds_read_b128 v[202:205], v221 offset:7168
	buffer_load_dwordx4 v178, s[76:79], s7 offen lds
	s_mov_b32 m0, s22
	s_nop 0
	buffer_load_dwordx4 v210, s[76:79], s7 offen lds
	s_waitcnt vmcnt(8)
	s_waitcnt lgkmcnt(0)
	s_setprio 1
	s_barrier
	v_mfma_f32_16x16x32_bf16 v[126:129], v[130:133], v[162:165], v[126:129]
	v_mfma_f32_16x16x32_bf16 v[126:129], v[134:137], v[170:173], v[126:129]
	v_mfma_f32_16x16x32_bf16 v[110:113], v[138:141], v[162:165], v[110:113]
	v_mfma_f32_16x16x32_bf16 v[110:113], v[142:145], v[170:173], v[110:113]
	v_mfma_f32_16x16x32_bf16 v[102:105], v[138:141], v[182:185], v[102:105]
	v_mfma_f32_16x16x32_bf16 v[102:105], v[142:145], v[186:189], v[102:105]
	v_mfma_f32_16x16x32_bf16 v[118:121], v[130:133], v[182:185], v[118:121]
	v_mfma_f32_16x16x32_bf16 v[118:121], v[134:137], v[186:189], v[118:121]
	v_mfma_f32_16x16x32_bf16 v[114:117], v[130:133], v[190:193], v[114:117]
	v_mfma_f32_16x16x32_bf16 v[114:117], v[134:137], v[194:197], v[114:117]
	v_mfma_f32_16x16x32_bf16 v[98:101], v[138:141], v[190:193], v[98:101]
	v_mfma_f32_16x16x32_bf16 v[98:101], v[142:145], v[194:197], v[98:101]
	v_mfma_f32_16x16x32_bf16 v[106:109], v[138:141], v[198:201], v[106:109]
	v_mfma_f32_16x16x32_bf16 v[106:109], v[142:145], v[202:205], v[106:109]
	v_mfma_f32_16x16x32_bf16 v[122:125], v[130:133], v[198:201], v[122:125]
	v_mfma_f32_16x16x32_bf16 v[122:125], v[134:137], v[202:205], v[122:125]
	v_mfma_f32_16x16x32_bf16 v[62:65], v[146:149], v[162:165], v[62:65]
	v_mfma_f32_16x16x32_bf16 v[62:65], v[150:153], v[170:173], v[62:65]
	v_mfma_f32_16x16x32_bf16 v[46:49], v[154:157], v[162:165], v[46:49]
	v_mfma_f32_16x16x32_bf16 v[46:49], v[158:161], v[170:173], v[46:49]
	v_mfma_f32_16x16x32_bf16 v[38:41], v[154:157], v[182:185], v[38:41]
	v_mfma_f32_16x16x32_bf16 v[38:41], v[158:161], v[186:189], v[38:41]
	v_mfma_f32_16x16x32_bf16 v[54:57], v[146:149], v[182:185], v[54:57]
	v_mfma_f32_16x16x32_bf16 v[54:57], v[150:153], v[186:189], v[54:57]
	v_mfma_f32_16x16x32_bf16 v[50:53], v[146:149], v[190:193], v[50:53]
	v_mfma_f32_16x16x32_bf16 v[50:53], v[150:153], v[194:197], v[50:53]
	v_mfma_f32_16x16x32_bf16 v[34:37], v[154:157], v[190:193], v[34:37]
	v_mfma_f32_16x16x32_bf16 v[34:37], v[158:161], v[194:197], v[34:37]
	v_mfma_f32_16x16x32_bf16 v[42:45], v[154:157], v[198:201], v[42:45]
	v_mfma_f32_16x16x32_bf16 v[42:45], v[158:161], v[202:205], v[42:45]
	v_mfma_f32_16x16x32_bf16 v[58:61], v[146:149], v[198:201], v[58:61]
	v_mfma_f32_16x16x32_bf16 v[58:61], v[150:153], v[202:205], v[58:61]
	s_barrier
	s_setprio 0
	s_mov_b32 m0, s90
	s_mov_b32 s58, s78
	s_mov_b32 s59, s79
	ds_read_b128 v[162:165], v221 offset:16384
	ds_read_b128 v[170:173], v221 offset:17408
	ds_read_b128 v[182:185], v221 offset:18432
	ds_read_b128 v[186:189], v221 offset:19456
	ds_read_b128 v[190:193], v221 offset:20480
	ds_read_b128 v[194:197], v221 offset:21504
	ds_read_b128 v[198:201], v221 offset:22528
	ds_read_b128 v[202:205], v221 offset:23552
	buffer_load_dwordx4 v179, s[56:59], s31 offen lds
	s_mov_b32 m0, s91
	s_add_i32 s51, s31, 0x80000
	buffer_load_dwordx4 v211, s[56:59], s31 offen lds
	s_mov_b32 m0, s9
	s_nop 0
	buffer_load_dwordx4 v179, s[56:59], s51 offen lds
	s_mov_b32 m0, s10
	s_nop 0
	buffer_load_dwordx4 v211, s[56:59], s51 offen lds
	s_mov_b32 m0, s89
	s_nop 0
	buffer_load_dwordx4 v178, s[76:79], s50 offen lds
	s_mov_b32 m0, s11
	s_nop 0
	buffer_load_dwordx4 v210, s[76:79], s50 offen lds
	s_waitcnt vmcnt(8)
	s_waitcnt lgkmcnt(0)
	s_setprio 1
	s_barrier
	v_mfma_f32_16x16x32_bf16 v[94:97], v[130:133], v[162:165], v[94:97]
	v_mfma_f32_16x16x32_bf16 v[94:97], v[134:137], v[170:173], v[94:97]
	v_mfma_f32_16x16x32_bf16 v[78:81], v[138:141], v[162:165], v[78:81]
	v_mfma_f32_16x16x32_bf16 v[78:81], v[142:145], v[170:173], v[78:81]
	v_mfma_f32_16x16x32_bf16 v[70:73], v[138:141], v[182:185], v[70:73]
	v_mfma_f32_16x16x32_bf16 v[70:73], v[142:145], v[186:189], v[70:73]
	v_mfma_f32_16x16x32_bf16 v[86:89], v[130:133], v[182:185], v[86:89]
	v_mfma_f32_16x16x32_bf16 v[86:89], v[134:137], v[186:189], v[86:89]
	v_mfma_f32_16x16x32_bf16 v[82:85], v[130:133], v[190:193], v[82:85]
	v_mfma_f32_16x16x32_bf16 v[82:85], v[134:137], v[194:197], v[82:85]
	v_mfma_f32_16x16x32_bf16 v[66:69], v[138:141], v[190:193], v[66:69]
	v_mfma_f32_16x16x32_bf16 v[66:69], v[142:145], v[194:197], v[66:69]
	v_mfma_f32_16x16x32_bf16 v[74:77], v[138:141], v[198:201], v[74:77]
	v_mfma_f32_16x16x32_bf16 v[74:77], v[142:145], v[202:205], v[74:77]
	v_mfma_f32_16x16x32_bf16 v[90:93], v[130:133], v[198:201], v[90:93]
	v_mfma_f32_16x16x32_bf16 v[90:93], v[134:137], v[202:205], v[90:93]
	v_mfma_f32_16x16x32_bf16 v[30:33], v[146:149], v[162:165], v[30:33]
	v_mfma_f32_16x16x32_bf16 v[30:33], v[150:153], v[170:173], v[30:33]
	v_mfma_f32_16x16x32_bf16 v[14:17], v[154:157], v[162:165], v[14:17]
	v_mfma_f32_16x16x32_bf16 v[14:17], v[158:161], v[170:173], v[14:17]
	v_mfma_f32_16x16x32_bf16 v[10:13], v[154:157], v[182:185], v[10:13]
	v_mfma_f32_16x16x32_bf16 v[10:13], v[158:161], v[186:189], v[10:13]
	v_mfma_f32_16x16x32_bf16 v[22:25], v[146:149], v[182:185], v[22:25]
	v_mfma_f32_16x16x32_bf16 v[22:25], v[150:153], v[186:189], v[22:25]
	v_mfma_f32_16x16x32_bf16 v[18:21], v[146:149], v[190:193], v[18:21]
	v_mfma_f32_16x16x32_bf16 v[18:21], v[150:153], v[194:197], v[18:21]
	v_mfma_f32_16x16x32_bf16 v[2:5], v[154:157], v[190:193], v[2:5]
	v_mfma_f32_16x16x32_bf16 v[2:5], v[158:161], v[194:197], v[2:5]
	v_mfma_f32_16x16x32_bf16 v[6:9], v[154:157], v[198:201], v[6:9]
	v_mfma_f32_16x16x32_bf16 v[6:9], v[158:161], v[202:205], v[6:9]
	v_mfma_f32_16x16x32_bf16 v[26:29], v[146:149], v[198:201], v[26:29]
	v_mfma_f32_16x16x32_bf16 v[26:29], v[150:153], v[202:205], v[26:29]
	s_barrier
; #define PG8_STAGEX(rs, bufoff, soff, voff) do { _Pragma("unroll") for (int _i = 0; _i < 2; ++_i) \
;         __builtin_amdgcn_raw_ptr_buffer_load_lds(rs, (LAS unsigned*)(lds + (bufoff) + ldsw + _i * 8192), 16, (voff)[_i], (soff), 0, 0); } while (0)
; #define PG8_LDA(dst, b, h) do { _Pragma("unroll") for (int m = 0; m < 4; ++m) _Pragma("unroll") for (int k = 0; k < 2; ++k) dst[m][k] = *(const LAS bf16x8*)(lds + PG8_SA(b, h) + aoff + m * 2048 + k * 1024); } while (0)
; #define PG8_LDB(dst, b, h) do { _Pragma("unroll") for (int n = 0; n < 2; ++n) _Pragma("unroll") for (int k = 0; k < 2; ++k) dst[n][k] = *(const LAS bf16x8*)(lds + PG8_SB(b, h) + boff + n * 2048 + k * 1024); } while (0)
; #define PG8_WAIT_V(n) asm volatile("s_waitcnt vmcnt(" #n ")" ::: "memory")
; #define PG8_WAIT_L(n) asm volatile("s_waitcnt lgkmcnt(" #n ")" ::: "memory")
; #define PG8_BAR __builtin_amdgcn_s_barrier()
; #define PG8_SCHED __builtin_amdgcn_sched_barrier(0)
;     ...
;             PG8_LDB(B0, 1, 0); PG8_LDB(B1, 1, 1); PG8_SCHED; PG8_LDA(At, 1, 0); PG8_STAGEX(rsA, PG8_SA(0, 1), a2 + hstepA, voffA);
;             PG8_WAIT_V(8); PG8_WAIT_L(0); PG8_BAR; PG8_MMA(0, 0, At, B0); PG8_MMA(0, 1, At, B1); PG8_BAR; PG8_SCHED;
;             PG8_LDA(At, 1, 1); PG8_STAGEX(rsB, PG8_SB(1, 0), b3, voffB); PG8_STAGEX(rsB, PG8_SB(1, 1), b3 + hstepB, voffB); PG8_STAGEX(rsA, PG8_SA(1, 0), a3, voffA);
;             PG8_WAIT_V(8); PG8_WAIT_L(0); PG8_BAR; PG8_MMA(1, 0, At, B0); PG8_MMA(1, 1, At, B1); PG8_BAR; PG8_SCHED;
;     ...
;         if (wr == 0) PG8_BAR;
	s_setprio 0
	v_add_u32_e32 v142, 0x18000, v220
	v_add_u32_e32 v158, 0x1c000, v220
	ds_read_b128 v[130:133], v142
	ds_read_b128 v[134:137], v142 offset:1024
	ds_read_b128 v[138:141], v142 offset:2048
	ds_read_b128 v[142:145], v142 offset:3072
	ds_read_b128 v[146:149], v158
	ds_read_b128 v[150:153], v158 offset:1024
	ds_read_b128 v[154:157], v158 offset:2048
	ds_read_b128 v[158:161], v158 offset:3072
	s_add_i32 s50, s50, 0x80000
	s_mov_b32 m0, s74
	ds_read_b128 v[162:165], v221 offset:32768
	ds_read_b128 v[170:173], v221 offset:33792
	ds_read_b128 v[182:185], v221 offset:34816
	ds_read_b128 v[186:189], v221 offset:35840
	ds_read_b128 v[190:193], v221 offset:36864
	ds_read_b128 v[194:197], v221 offset:37888
	ds_read_b128 v[198:201], v221 offset:38912
	ds_read_b128 v[202:205], v221 offset:39936
	buffer_load_dwordx4 v178, s[76:79], s50 offen lds
	s_mov_b32 m0, s12
	s_nop 0
	buffer_load_dwordx4 v210, s[76:79], s50 offen lds
	s_waitcnt vmcnt(8)
	s_waitcnt lgkmcnt(0)
	s_setprio 1
	s_barrier
	v_mfma_f32_16x16x32_bf16 v[126:129], v[130:133], v[162:165], v[126:129]
	v_mfma_f32_16x16x32_bf16 v[126:129], v[134:137], v[170:173], v[126:129]
	v_mfma_f32_16x16x32_bf16 v[110:113], v[138:141], v[162:165], v[110:113]
	v_mfma_f32_16x16x32_bf16 v[110:113], v[142:145], v[170:173], v[110:113]
	v_mfma_f32_16x16x32_bf16 v[102:105], v[138:141], v[182:185], v[102:105]
	v_mfma_f32_16x16x32_bf16 v[102:105], v[142:145], v[186:189], v[102:105]
	v_mfma_f32_16x16x32_bf16 v[118:121], v[130:133], v[182:185], v[118:121]
	v_mfma_f32_16x16x32_bf16 v[118:121], v[134:137], v[186:189], v[118:121]
	v_mfma_f32_16x16x32_bf16 v[114:117], v[130:133], v[190:193], v[114:117]
	v_mfma_f32_16x16x32_bf16 v[114:117], v[134:137], v[194:197], v[114:117]
	v_mfma_f32_16x16x32_bf16 v[98:101], v[138:141], v[190:193], v[98:101]
	v_mfma_f32_16x16x32_bf16 v[98:101], v[142:145], v[194:197], v[98:101]
	v_mfma_f32_16x16x32_bf16 v[106:109], v[138:141], v[198:201], v[106:109]
	v_mfma_f32_16x16x32_bf16 v[106:109], v[142:145], v[202:205], v[106:109]
	v_mfma_f32_16x16x32_bf16 v[122:125], v[130:133], v[198:201], v[122:125]
	v_mfma_f32_16x16x32_bf16 v[122:125], v[134:137], v[202:205], v[122:125]
	v_mfma_f32_16x16x32_bf16 v[62:65], v[146:149], v[162:165], v[62:65]
	v_mfma_f32_16x16x32_bf16 v[62:65], v[150:153], v[170:173], v[62:65]
	v_mfma_f32_16x16x32_bf16 v[46:49], v[154:157], v[162:165], v[46:49]
	v_mfma_f32_16x16x32_bf16 v[46:49], v[158:161], v[170:173], v[46:49]
	v_mfma_f32_16x16x32_bf16 v[38:41], v[154:157], v[182:185], v[38:41]
	v_mfma_f32_16x16x32_bf16 v[38:41], v[158:161], v[186:189], v[38:41]
	v_mfma_f32_16x16x32_bf16 v[54:57], v[146:149], v[182:185], v[54:57]
	v_mfma_f32_16x16x32_bf16 v[54:57], v[150:153], v[186:189], v[54:57]
	v_mfma_f32_16x16x32_bf16 v[50:53], v[146:149], v[190:193], v[50:53]
	v_mfma_f32_16x16x32_bf16 v[50:53], v[150:153], v[194:197], v[50:53]
	v_mfma_f32_16x16x32_bf16 v[34:37], v[154:157], v[190:193], v[34:37]
	v_mfma_f32_16x16x32_bf16 v[34:37], v[158:161], v[194:197], v[34:37]
	v_mfma_f32_16x16x32_bf16 v[42:45], v[154:157], v[198:201], v[42:45]
	v_mfma_f32_16x16x32_bf16 v[42:45], v[158:161], v[202:205], v[42:45]
	v_mfma_f32_16x16x32_bf16 v[58:61], v[146:149], v[198:201], v[58:61]
	v_mfma_f32_16x16x32_bf16 v[58:61], v[150:153], v[202:205], v[58:61]
	s_barrier
	s_setprio 0
	s_mov_b32 m0, s13
	s_or_b32 s50, s31, 0x80
	ds_read_b128 v[162:165], v221 offset:49152
	ds_read_b128 v[170:173], v221 offset:50176
	ds_read_b128 v[182:185], v221 offset:51200
	ds_read_b128 v[186:189], v221 offset:52224
	ds_read_b128 v[190:193], v221 offset:53248
	ds_read_b128 v[194:197], v221 offset:54272
	ds_read_b128 v[198:201], v221 offset:55296
	ds_read_b128 v[202:205], v221 offset:56320
	buffer_load_dwordx4 v179, s[56:59], s50 offen lds
	s_mov_b32 m0, s14
	s_add_i32 s31, s31, 0x80080
	buffer_load_dwordx4 v211, s[56:59], s50 offen lds
	s_mov_b32 m0, s17
	s_nop 0
	buffer_load_dwordx4 v179, s[56:59], s31 offen lds
	s_mov_b32 m0, s18
	s_nop 0
	buffer_load_dwordx4 v211, s[56:59], s31 offen lds
	s_mov_b32 m0, s15
	s_cmp_eq_u32 s29, 28
	buffer_load_dwordx4 v178, s[76:79], s30 offen lds
	s_mov_b32 m0, s16
	s_cselect_b64 vcc, s[70:71], 0
	buffer_load_dwordx4 v210, s[76:79], s30 offen lds
	s_waitcnt vmcnt(8)
	s_waitcnt lgkmcnt(0)
	s_setprio 1
	s_barrier
	v_mfma_f32_16x16x32_bf16 v[94:97], v[130:133], v[162:165], v[94:97]
	v_mfma_f32_16x16x32_bf16 v[94:97], v[134:137], v[170:173], v[94:97]
	v_mfma_f32_16x16x32_bf16 v[78:81], v[138:141], v[162:165], v[78:81]
	v_mfma_f32_16x16x32_bf16 v[78:81], v[142:145], v[170:173], v[78:81]
	v_mfma_f32_16x16x32_bf16 v[70:73], v[138:141], v[182:185], v[70:73]
	v_mfma_f32_16x16x32_bf16 v[70:73], v[142:145], v[186:189], v[70:73]
	v_mfma_f32_16x16x32_bf16 v[86:89], v[130:133], v[182:185], v[86:89]
	v_mfma_f32_16x16x32_bf16 v[86:89], v[134:137], v[186:189], v[86:89]
	v_mfma_f32_16x16x32_bf16 v[82:85], v[130:133], v[190:193], v[82:85]
	v_mfma_f32_16x16x32_bf16 v[82:85], v[134:137], v[194:197], v[82:85]
	v_mfma_f32_16x16x32_bf16 v[66:69], v[138:141], v[190:193], v[66:69]
	v_mfma_f32_16x16x32_bf16 v[66:69], v[142:145], v[194:197], v[66:69]
	v_mfma_f32_16x16x32_bf16 v[74:77], v[138:141], v[198:201], v[74:77]
	v_mfma_f32_16x16x32_bf16 v[74:77], v[142:145], v[202:205], v[74:77]
	v_mfma_f32_16x16x32_bf16 v[90:93], v[130:133], v[198:201], v[90:93]
	v_mfma_f32_16x16x32_bf16 v[90:93], v[134:137], v[202:205], v[90:93]
	v_mfma_f32_16x16x32_bf16 v[30:33], v[146:149], v[162:165], v[30:33]
	v_mfma_f32_16x16x32_bf16 v[30:33], v[150:153], v[170:173], v[30:33]
	v_mfma_f32_16x16x32_bf16 v[14:17], v[154:157], v[162:165], v[14:17]
	v_mfma_f32_16x16x32_bf16 v[14:17], v[158:161], v[170:173], v[14:17]
	v_mfma_f32_16x16x32_bf16 v[10:13], v[154:157], v[182:185], v[10:13]
	v_mfma_f32_16x16x32_bf16 v[10:13], v[158:161], v[186:189], v[10:13]
	v_mfma_f32_16x16x32_bf16 v[22:25], v[146:149], v[182:185], v[22:25]
	v_mfma_f32_16x16x32_bf16 v[22:25], v[150:153], v[186:189], v[22:25]
	v_mfma_f32_16x16x32_bf16 v[18:21], v[146:149], v[190:193], v[18:21]
	v_mfma_f32_16x16x32_bf16 v[18:21], v[150:153], v[194:197], v[18:21]
	v_mfma_f32_16x16x32_bf16 v[2:5], v[154:157], v[190:193], v[2:5]
	v_mfma_f32_16x16x32_bf16 v[2:5], v[158:161], v[194:197], v[2:5]
	v_mfma_f32_16x16x32_bf16 v[6:9], v[154:157], v[198:201], v[6:9]
	v_mfma_f32_16x16x32_bf16 v[6:9], v[158:161], v[202:205], v[6:9]
	v_mfma_f32_16x16x32_bf16 v[26:29], v[146:149], v[198:201], v[26:29]
	v_mfma_f32_16x16x32_bf16 v[26:29], v[150:153], v[202:205], v[26:29]
	s_cbranch_vccnz .Lee_skip_437
	s_barrier
.Lee_skip_437:
	s_setprio 0
	s_add_i32 s29, s29, 2
	s_addk_i32 s7, 0x100
	s_addk_i32 s28, 0x100
	s_cmp_gt_u32 s29, 29
	s_cbranch_scc0 .LBB0_437

; #define PG8_STAGEX(rs, bufoff, soff, voff) do { _Pragma("unroll") for (int _i = 0; _i < 2; ++_i) \
;         __builtin_amdgcn_raw_ptr_buffer_load_lds(rs, (LAS unsigned*)(lds + (bufoff) + ldsw + _i * 8192), 16, (voff)[_i], (soff), 0, 0); } while (0)
; #define PG8_LDA(dst, b, h) do { _Pragma("unroll") for (int m = 0; m < 4; ++m) _Pragma("unroll") for (int k = 0; k < 2; ++k) dst[m][k] = *(const LAS bf16x8*)(lds + PG8_SA(b, h) + aoff + m * 2048 + k * 1024); } while (0)
; #define PG8_LDB(dst, b, h) do { _Pragma("unroll") for (int n = 0; n < 2; ++n) _Pragma("unroll") for (int k = 0; k < 2; ++k) dst[n][k] = *(const LAS bf16x8*)(lds + PG8_SB(b, h) + boff + n * 2048 + k * 1024); } while (0)
; #define PG8_WAIT_V(n) asm volatile("s_waitcnt vmcnt(" #n ")" ::: "memory")
; #define PG8_WAIT_L(n) asm volatile("s_waitcnt lgkmcnt(" #n ")" ::: "memory")
; #define PG8_BAR __builtin_amdgcn_s_barrier()
; #define PG8_SCHED __builtin_amdgcn_sched_barrier(0)
;     ...
;             PG8_LDB(B0, 0, 0); PG8_LDB(B1, 0, 1); PG8_SCHED; PG8_LDA(At, 0, 0); PG8_STAGEX(rsA, PG8_SA(1, 1), a1 + hstepA, voffA);
;             PG8_WAIT_V(8); PG8_WAIT_L(0); PG8_BAR; PG8_MMA(0, 0, At, B0); PG8_MMA(0, 1, At, B1); PG8_BAR; PG8_SCHED;
;             PG8_LDA(At, 0, 1); PG8_STAGEX(rsB, PG8_SB(0, 0), b2, voffB); PG8_STAGEX(rsB, PG8_SB(0, 1), b2 + hstepB, voffB); PG8_STAGEX(rsA, PG8_SA(0, 0), a2, voffA);
;             PG8_WAIT_V(8); PG8_WAIT_L(0); PG8_BAR; PG8_MMA(1, 0, At, B0); PG8_MMA(1, 1, At, B1); PG8_BAR; PG8_SCHED;
.LBB0_1274:
	v_add_u32_e32 v142, 0x10000, v157
	v_add_u32_e32 v159, 0x14000, v157
	ds_read_b128 v[130:133], v142
	ds_read_b128 v[134:137], v142 offset:1024
	ds_read_b128 v[138:141], v142 offset:2048
	ds_read_b128 v[142:145], v142 offset:3072
	ds_read_b128 v[146:149], v159
	ds_read_b128 v[164:167], v159 offset:1024
	ds_read_b128 v[168:171], v159 offset:2048
	ds_read_b128 v[182:185], v159 offset:3072
	s_add_i32 s42, s62, 0xfff80080
	s_cmp_eq_u32 s67, 28
	s_cselect_b32 s70, s30, s42
	s_cselect_b32 s69, s31, s63
	s_or_b32 s68, s70, 0x80
	s_mov_b32 m0, s29
	ds_read_b128 v[186:189], v158
	ds_read_b128 v[190:193], v158 offset:1024
	ds_read_b128 v[194:197], v158 offset:2048
	ds_read_b128 v[198:201], v158 offset:3072
	ds_read_b128 v[202:205], v158 offset:4096
	ds_read_b128 v[206:209], v158 offset:5120
	ds_read_b128 v[210:213], v158 offset:6144
	ds_read_b128 v[214:217], v158 offset:7168
	buffer_load_dwordx4 v150, s[76:79], s62 offen lds
	s_mov_b32 m0, s35
	s_nop 0
	buffer_load_dwordx4 v152, s[76:79], s62 offen lds
	s_waitcnt vmcnt(8)
	s_waitcnt lgkmcnt(0)
	s_setprio 1
	s_barrier
	v_mfma_f32_16x16x32_bf16 v[126:129], v[130:133], v[186:189], v[126:129]
	v_mfma_f32_16x16x32_bf16 v[126:129], v[134:137], v[190:193], v[126:129]
	v_mfma_f32_16x16x32_bf16 v[122:125], v[138:141], v[186:189], v[122:125]
	v_mfma_f32_16x16x32_bf16 v[122:125], v[142:145], v[190:193], v[122:125]
	v_mfma_f32_16x16x32_bf16 v[114:117], v[138:141], v[194:197], v[114:117]
	v_mfma_f32_16x16x32_bf16 v[114:117], v[142:145], v[198:201], v[114:117]
	v_mfma_f32_16x16x32_bf16 v[118:121], v[130:133], v[194:197], v[118:121]
	v_mfma_f32_16x16x32_bf16 v[118:121], v[134:137], v[198:201], v[118:121]
	v_mfma_f32_16x16x32_bf16 v[110:113], v[130:133], v[202:205], v[110:113]
	v_mfma_f32_16x16x32_bf16 v[110:113], v[134:137], v[206:209], v[110:113]
	v_mfma_f32_16x16x32_bf16 v[106:109], v[138:141], v[202:205], v[106:109]
	v_mfma_f32_16x16x32_bf16 v[106:109], v[142:145], v[206:209], v[106:109]
	v_mfma_f32_16x16x32_bf16 v[98:101], v[138:141], v[210:213], v[98:101]
	v_mfma_f32_16x16x32_bf16 v[98:101], v[142:145], v[214:217], v[98:101]
	v_mfma_f32_16x16x32_bf16 v[102:105], v[130:133], v[210:213], v[102:105]
	v_mfma_f32_16x16x32_bf16 v[102:105], v[134:137], v[214:217], v[102:105]
	v_mfma_f32_16x16x32_bf16 v[62:65], v[146:149], v[186:189], v[62:65]
	v_mfma_f32_16x16x32_bf16 v[62:65], v[164:167], v[190:193], v[62:65]
	v_mfma_f32_16x16x32_bf16 v[58:61], v[168:171], v[186:189], v[58:61]
	v_mfma_f32_16x16x32_bf16 v[58:61], v[182:185], v[190:193], v[58:61]
	v_mfma_f32_16x16x32_bf16 v[50:53], v[168:171], v[194:197], v[50:53]
	v_mfma_f32_16x16x32_bf16 v[50:53], v[182:185], v[198:201], v[50:53]
	v_mfma_f32_16x16x32_bf16 v[54:57], v[146:149], v[194:197], v[54:57]
	v_mfma_f32_16x16x32_bf16 v[54:57], v[164:167], v[198:201], v[54:57]
	v_mfma_f32_16x16x32_bf16 v[46:49], v[146:149], v[202:205], v[46:49]
	v_mfma_f32_16x16x32_bf16 v[46:49], v[164:167], v[206:209], v[46:49]
	v_mfma_f32_16x16x32_bf16 v[42:45], v[168:171], v[202:205], v[42:45]
	v_mfma_f32_16x16x32_bf16 v[42:45], v[182:185], v[206:209], v[42:45]
	v_mfma_f32_16x16x32_bf16 v[34:37], v[168:171], v[210:213], v[34:37]
	v_mfma_f32_16x16x32_bf16 v[34:37], v[182:185], v[214:217], v[34:37]
	v_mfma_f32_16x16x32_bf16 v[38:41], v[146:149], v[210:213], v[38:41]
	v_mfma_f32_16x16x32_bf16 v[38:41], v[164:167], v[214:217], v[38:41]
	s_barrier
	s_setprio 0
	s_mov_b32 m0, s16
	s_mov_b32 s42, s78
	s_mov_b32 s43, s79
	ds_read_b128 v[186:189], v158 offset:16384
	ds_read_b128 v[190:193], v158 offset:17408
	ds_read_b128 v[194:197], v158 offset:18432
	ds_read_b128 v[198:201], v158 offset:19456
	ds_read_b128 v[202:205], v158 offset:20480
	ds_read_b128 v[206:209], v158 offset:21504
	ds_read_b128 v[210:213], v158 offset:22528
	ds_read_b128 v[214:217], v158 offset:23552
	buffer_load_dwordx4 v151, s[40:43], s69 offen lds
	s_mov_b32 m0, s17
	s_add_i32 s71, s69, 0x80000
	buffer_load_dwordx4 v153, s[40:43], s69 offen lds
	s_mov_b32 m0, s18
	s_nop 0
	buffer_load_dwordx4 v151, s[40:43], s71 offen lds
	s_mov_b32 m0, s19
	s_nop 0
	buffer_load_dwordx4 v153, s[40:43], s71 offen lds
	s_mov_b32 m0, s15
	s_nop 0
	buffer_load_dwordx4 v150, s[76:79], s70 offen lds
	s_mov_b32 m0, s20
	s_nop 0
	buffer_load_dwordx4 v152, s[76:79], s70 offen lds
	s_waitcnt vmcnt(8)
	s_waitcnt lgkmcnt(0)
	s_setprio 1
	s_barrier
	v_mfma_f32_16x16x32_bf16 v[94:97], v[130:133], v[186:189], v[94:97]
	v_mfma_f32_16x16x32_bf16 v[94:97], v[134:137], v[190:193], v[94:97]
	v_mfma_f32_16x16x32_bf16 v[90:93], v[138:141], v[186:189], v[90:93]
	v_mfma_f32_16x16x32_bf16 v[90:93], v[142:145], v[190:193], v[90:93]
	v_mfma_f32_16x16x32_bf16 v[82:85], v[138:141], v[194:197], v[82:85]
	v_mfma_f32_16x16x32_bf16 v[82:85], v[142:145], v[198:201], v[82:85]
	v_mfma_f32_16x16x32_bf16 v[86:89], v[130:133], v[194:197], v[86:89]
	v_mfma_f32_16x16x32_bf16 v[86:89], v[134:137], v[198:201], v[86:89]
	v_mfma_f32_16x16x32_bf16 v[78:81], v[130:133], v[202:205], v[78:81]
	v_mfma_f32_16x16x32_bf16 v[78:81], v[134:137], v[206:209], v[78:81]
	v_mfma_f32_16x16x32_bf16 v[74:77], v[138:141], v[202:205], v[74:77]
	v_mfma_f32_16x16x32_bf16 v[74:77], v[142:145], v[206:209], v[74:77]
	v_mfma_f32_16x16x32_bf16 v[66:69], v[138:141], v[210:213], v[66:69]
	v_mfma_f32_16x16x32_bf16 v[66:69], v[142:145], v[214:217], v[66:69]
	v_mfma_f32_16x16x32_bf16 v[70:73], v[130:133], v[210:213], v[70:73]
	v_mfma_f32_16x16x32_bf16 v[70:73], v[134:137], v[214:217], v[70:73]
	v_mfma_f32_16x16x32_bf16 v[30:33], v[146:149], v[186:189], v[30:33]
	v_mfma_f32_16x16x32_bf16 v[30:33], v[164:167], v[190:193], v[30:33]
	v_mfma_f32_16x16x32_bf16 v[26:29], v[168:171], v[186:189], v[26:29]
	v_mfma_f32_16x16x32_bf16 v[26:29], v[182:185], v[190:193], v[26:29]
	v_mfma_f32_16x16x32_bf16 v[18:21], v[168:171], v[194:197], v[18:21]
	v_mfma_f32_16x16x32_bf16 v[18:21], v[182:185], v[198:201], v[18:21]
	v_mfma_f32_16x16x32_bf16 v[22:25], v[146:149], v[194:197], v[22:25]
	v_mfma_f32_16x16x32_bf16 v[22:25], v[164:167], v[198:201], v[22:25]
	v_mfma_f32_16x16x32_bf16 v[14:17], v[146:149], v[202:205], v[14:17]
	v_mfma_f32_16x16x32_bf16 v[14:17], v[164:167], v[206:209], v[14:17]
	v_mfma_f32_16x16x32_bf16 v[10:13], v[168:171], v[202:205], v[10:13]
	v_mfma_f32_16x16x32_bf16 v[10:13], v[182:185], v[206:209], v[10:13]
	v_mfma_f32_16x16x32_bf16 v[2:5], v[168:171], v[210:213], v[2:5]
	v_mfma_f32_16x16x32_bf16 v[2:5], v[182:185], v[214:217], v[2:5]
	v_mfma_f32_16x16x32_bf16 v[6:9], v[146:149], v[210:213], v[6:9]
	v_mfma_f32_16x16x32_bf16 v[6:9], v[164:167], v[214:217], v[6:9]
	s_barrier
; #define PG8_STAGEX(rs, bufoff, soff, voff) do { _Pragma("unroll") for (int _i = 0; _i < 2; ++_i) \
;         __builtin_amdgcn_raw_ptr_buffer_load_lds(rs, (LAS unsigned*)(lds + (bufoff) + ldsw + _i * 8192), 16, (voff)[_i], (soff), 0, 0); } while (0)
; #define PG8_LDA(dst, b, h) do { _Pragma("unroll") for (int m = 0; m < 4; ++m) _Pragma("unroll") for (int k = 0; k < 2; ++k) dst[m][k] = *(const LAS bf16x8*)(lds + PG8_SA(b, h) + aoff + m * 2048 + k * 1024); } while (0)
; #define PG8_LDB(dst, b, h) do { _Pragma("unroll") for (int n = 0; n < 2; ++n) _Pragma("unroll") for (int k = 0; k < 2; ++k) dst[n][k] = *(const LAS bf16x8*)(lds + PG8_SB(b, h) + boff + n * 2048 + k * 1024); } while (0)
; #define PG8_WAIT_V(n) asm volatile("s_waitcnt vmcnt(" #n ")" ::: "memory")
; #define PG8_WAIT_L(n) asm volatile("s_waitcnt lgkmcnt(" #n ")" ::: "memory")
; #define PG8_BAR __builtin_amdgcn_s_barrier()
; #define PG8_SCHED __builtin_amdgcn_sched_barrier(0)
;     ...
;             PG8_LDB(B0, 1, 0); PG8_LDB(B1, 1, 1); PG8_SCHED; PG8_LDA(At, 1, 0); PG8_STAGEX(rsA, PG8_SA(0, 1), a2 + hstepA, voffA);
;             PG8_WAIT_V(8); PG8_WAIT_L(0); PG8_BAR; PG8_MMA(0, 0, At, B0); PG8_MMA(0, 1, At, B1); PG8_BAR; PG8_SCHED;
;             PG8_LDA(At, 1, 1); PG8_STAGEX(rsB, PG8_SB(1, 0), b3, voffB); PG8_STAGEX(rsB, PG8_SB(1, 1), b3 + hstepB, voffB); PG8_STAGEX(rsA, PG8_SA(1, 0), a3, voffA);
;             PG8_WAIT_V(8); PG8_WAIT_L(0); PG8_BAR; PG8_MMA(1, 0, At, B0); PG8_MMA(1, 1, At, B1); PG8_BAR; PG8_SCHED;
;     ...
;         if (wr == 0) PG8_BAR;
	s_setprio 0
	v_add_u32_e32 v142, 0x18000, v157
	v_add_u32_e32 v159, 0x1c000, v157
	ds_read_b128 v[130:133], v142
	ds_read_b128 v[134:137], v142 offset:1024
	ds_read_b128 v[138:141], v142 offset:2048
	ds_read_b128 v[142:145], v142 offset:3072
	ds_read_b128 v[146:149], v159
	ds_read_b128 v[164:167], v159 offset:1024
	ds_read_b128 v[168:171], v159 offset:2048
	ds_read_b128 v[182:185], v159 offset:3072
	s_add_i32 s70, s70, 0x80000
	s_mov_b32 m0, s21
	ds_read_b128 v[186:189], v158 offset:32768
	ds_read_b128 v[190:193], v158 offset:33792
	ds_read_b128 v[194:197], v158 offset:34816
	ds_read_b128 v[198:201], v158 offset:35840
	ds_read_b128 v[202:205], v158 offset:36864
	ds_read_b128 v[206:209], v158 offset:37888
	ds_read_b128 v[210:213], v158 offset:38912
	ds_read_b128 v[214:217], v158 offset:39936
	buffer_load_dwordx4 v150, s[76:79], s70 offen lds
	s_mov_b32 m0, s22
	s_nop 0
	buffer_load_dwordx4 v152, s[76:79], s70 offen lds
	s_waitcnt vmcnt(8)
	s_waitcnt lgkmcnt(0)
	s_setprio 1
	s_barrier
	v_mfma_f32_16x16x32_bf16 v[126:129], v[130:133], v[186:189], v[126:129]
	v_mfma_f32_16x16x32_bf16 v[126:129], v[134:137], v[190:193], v[126:129]
	v_mfma_f32_16x16x32_bf16 v[122:125], v[138:141], v[186:189], v[122:125]
	v_mfma_f32_16x16x32_bf16 v[122:125], v[142:145], v[190:193], v[122:125]
	v_mfma_f32_16x16x32_bf16 v[114:117], v[138:141], v[194:197], v[114:117]
	v_mfma_f32_16x16x32_bf16 v[114:117], v[142:145], v[198:201], v[114:117]
	v_mfma_f32_16x16x32_bf16 v[118:121], v[130:133], v[194:197], v[118:121]
	v_mfma_f32_16x16x32_bf16 v[118:121], v[134:137], v[198:201], v[118:121]
	v_mfma_f32_16x16x32_bf16 v[110:113], v[130:133], v[202:205], v[110:113]
	v_mfma_f32_16x16x32_bf16 v[110:113], v[134:137], v[206:209], v[110:113]
	v_mfma_f32_16x16x32_bf16 v[106:109], v[138:141], v[202:205], v[106:109]
	v_mfma_f32_16x16x32_bf16 v[106:109], v[142:145], v[206:209], v[106:109]
	v_mfma_f32_16x16x32_bf16 v[98:101], v[138:141], v[210:213], v[98:101]
	v_mfma_f32_16x16x32_bf16 v[98:101], v[142:145], v[214:217], v[98:101]
	v_mfma_f32_16x16x32_bf16 v[102:105], v[130:133], v[210:213], v[102:105]
	v_mfma_f32_16x16x32_bf16 v[102:105], v[134:137], v[214:217], v[102:105]
	v_mfma_f32_16x16x32_bf16 v[62:65], v[146:149], v[186:189], v[62:65]
	v_mfma_f32_16x16x32_bf16 v[62:65], v[164:167], v[190:193], v[62:65]
	v_mfma_f32_16x16x32_bf16 v[58:61], v[168:171], v[186:189], v[58:61]
	v_mfma_f32_16x16x32_bf16 v[58:61], v[182:185], v[190:193], v[58:61]
	v_mfma_f32_16x16x32_bf16 v[50:53], v[168:171], v[194:197], v[50:53]
	v_mfma_f32_16x16x32_bf16 v[50:53], v[182:185], v[198:201], v[50:53]
	v_mfma_f32_16x16x32_bf16 v[54:57], v[146:149], v[194:197], v[54:57]
	v_mfma_f32_16x16x32_bf16 v[54:57], v[164:167], v[198:201], v[54:57]
	v_mfma_f32_16x16x32_bf16 v[46:49], v[146:149], v[202:205], v[46:49]
	v_mfma_f32_16x16x32_bf16 v[46:49], v[164:167], v[206:209], v[46:49]
	v_mfma_f32_16x16x32_bf16 v[42:45], v[168:171], v[202:205], v[42:45]
	v_mfma_f32_16x16x32_bf16 v[42:45], v[182:185], v[206:209], v[42:45]
	v_mfma_f32_16x16x32_bf16 v[34:37], v[168:171], v[210:213], v[34:37]
	v_mfma_f32_16x16x32_bf16 v[34:37], v[182:185], v[214:217], v[34:37]
	v_mfma_f32_16x16x32_bf16 v[38:41], v[146:149], v[210:213], v[38:41]
	v_mfma_f32_16x16x32_bf16 v[38:41], v[164:167], v[214:217], v[38:41]
	s_barrier
	s_setprio 0
	s_mov_b32 m0, s23
	s_or_b32 s70, s69, 0x80
	ds_read_b128 v[186:189], v158 offset:49152
	ds_read_b128 v[190:193], v158 offset:50176
	ds_read_b128 v[194:197], v158 offset:51200
	ds_read_b128 v[198:201], v158 offset:52224
	ds_read_b128 v[202:205], v158 offset:53248
	ds_read_b128 v[206:209], v158 offset:54272
	ds_read_b128 v[210:213], v158 offset:55296
	ds_read_b128 v[214:217], v158 offset:56320
	buffer_load_dwordx4 v151, s[40:43], s70 offen lds
	s_mov_b32 m0, s24
	s_add_i32 s69, s69, 0x80080
	buffer_load_dwordx4 v153, s[40:43], s70 offen lds
	s_mov_b32 m0, s27
	s_nop 0
	buffer_load_dwordx4 v151, s[40:43], s69 offen lds
	s_mov_b32 m0, s28
	s_nop 0
	buffer_load_dwordx4 v153, s[40:43], s69 offen lds
	s_mov_b32 m0, s25
	s_cmp_eq_u32 s67, 28
	buffer_load_dwordx4 v150, s[76:79], s68 offen lds
	s_mov_b32 m0, s26
	s_cselect_b64 vcc, s[48:49], 0
	buffer_load_dwordx4 v152, s[76:79], s68 offen lds
	s_waitcnt vmcnt(8)
	s_waitcnt lgkmcnt(0)
	s_setprio 1
	s_barrier
	v_mfma_f32_16x16x32_bf16 v[94:97], v[130:133], v[186:189], v[94:97]
	v_mfma_f32_16x16x32_bf16 v[94:97], v[134:137], v[190:193], v[94:97]
	v_mfma_f32_16x16x32_bf16 v[90:93], v[138:141], v[186:189], v[90:93]
	v_mfma_f32_16x16x32_bf16 v[90:93], v[142:145], v[190:193], v[90:93]
	v_mfma_f32_16x16x32_bf16 v[82:85], v[138:141], v[194:197], v[82:85]
	v_mfma_f32_16x16x32_bf16 v[82:85], v[142:145], v[198:201], v[82:85]
	v_mfma_f32_16x16x32_bf16 v[86:89], v[130:133], v[194:197], v[86:89]
	v_mfma_f32_16x16x32_bf16 v[86:89], v[134:137], v[198:201], v[86:89]
	v_mfma_f32_16x16x32_bf16 v[78:81], v[130:133], v[202:205], v[78:81]
	v_mfma_f32_16x16x32_bf16 v[78:81], v[134:137], v[206:209], v[78:81]
	v_mfma_f32_16x16x32_bf16 v[74:77], v[138:141], v[202:205], v[74:77]
	v_mfma_f32_16x16x32_bf16 v[74:77], v[142:145], v[206:209], v[74:77]
	v_mfma_f32_16x16x32_bf16 v[66:69], v[138:141], v[210:213], v[66:69]
	v_mfma_f32_16x16x32_bf16 v[66:69], v[142:145], v[214:217], v[66:69]
	v_mfma_f32_16x16x32_bf16 v[70:73], v[130:133], v[210:213], v[70:73]
	v_mfma_f32_16x16x32_bf16 v[70:73], v[134:137], v[214:217], v[70:73]
	v_mfma_f32_16x16x32_bf16 v[30:33], v[146:149], v[186:189], v[30:33]
	v_mfma_f32_16x16x32_bf16 v[30:33], v[164:167], v[190:193], v[30:33]
	v_mfma_f32_16x16x32_bf16 v[26:29], v[168:171], v[186:189], v[26:29]
	v_mfma_f32_16x16x32_bf16 v[26:29], v[182:185], v[190:193], v[26:29]
	v_mfma_f32_16x16x32_bf16 v[18:21], v[168:171], v[194:197], v[18:21]
	v_mfma_f32_16x16x32_bf16 v[18:21], v[182:185], v[198:201], v[18:21]
	v_mfma_f32_16x16x32_bf16 v[22:25], v[146:149], v[194:197], v[22:25]
	v_mfma_f32_16x16x32_bf16 v[22:25], v[164:167], v[198:201], v[22:25]
	v_mfma_f32_16x16x32_bf16 v[14:17], v[146:149], v[202:205], v[14:17]
	v_mfma_f32_16x16x32_bf16 v[14:17], v[164:167], v[206:209], v[14:17]
	v_mfma_f32_16x16x32_bf16 v[10:13], v[168:171], v[202:205], v[10:13]
	v_mfma_f32_16x16x32_bf16 v[10:13], v[182:185], v[206:209], v[10:13]
	v_mfma_f32_16x16x32_bf16 v[2:5], v[168:171], v[210:213], v[2:5]
	v_mfma_f32_16x16x32_bf16 v[2:5], v[182:185], v[214:217], v[2:5]
	v_mfma_f32_16x16x32_bf16 v[6:9], v[146:149], v[210:213], v[6:9]
	v_mfma_f32_16x16x32_bf16 v[6:9], v[164:167], v[214:217], v[6:9]
	s_cbranch_vccnz .Lee_skip_1274
	s_barrier
.Lee_skip_1274:
	s_setprio 0
	s_add_i32 s67, s67, 2
	s_addk_i32 s62, 0x100
	s_addk_i32 s63, 0x100
	s_cmp_gt_u32 s67, 29
	s_cbranch_scc0 .LBB0_1274

; #define PG8_STAGEX(rs, bufoff, soff, voff) do { _Pragma("unroll") for (int _i = 0; _i < 2; ++_i) \
;         __builtin_amdgcn_raw_ptr_buffer_load_lds(rs, (LAS unsigned*)(lds + (bufoff) + ldsw + _i * 8192), 16, (voff)[_i], (soff), 0, 0); } while (0)
; #define PG8_LDA(dst, b, h) do { _Pragma("unroll") for (int m = 0; m < 4; ++m) _Pragma("unroll") for (int k = 0; k < 2; ++k) dst[m][k] = *(const LAS bf16x8*)(lds + PG8_SA(b, h) + aoff + m * 2048 + k * 1024); } while (0)
; #define PG8_LDB(dst, b, h) do { _Pragma("unroll") for (int n = 0; n < 2; ++n) _Pragma("unroll") for (int k = 0; k < 2; ++k) dst[n][k] = *(const LAS bf16x8*)(lds + PG8_SB(b, h) + boff + n * 2048 + k * 1024); } while (0)
; #define PG8_WAIT_V(n) asm volatile("s_waitcnt vmcnt(" #n ")" ::: "memory")
; #define PG8_WAIT_L(n) asm volatile("s_waitcnt lgkmcnt(" #n ")" ::: "memory")
; #define PG8_BAR __builtin_amdgcn_s_barrier()
; #define PG8_SCHED __builtin_amdgcn_sched_barrier(0)
;     ...
;             PG8_LDB(B0, 0, 0); PG8_LDB(B1, 0, 1); PG8_SCHED; PG8_LDA(At, 0, 0); PG8_STAGEX(rsA, PG8_SA(1, 1), a1 + hstepA, voffA);
;             PG8_WAIT_V(8); PG8_WAIT_L(0); PG8_BAR; PG8_MMA(0, 0, At, B0); PG8_MMA(0, 1, At, B1); PG8_BAR; PG8_SCHED;
;             PG8_LDA(At, 0, 1); PG8_STAGEX(rsB, PG8_SB(0, 0), b2, voffB); PG8_STAGEX(rsB, PG8_SB(0, 1), b2 + hstepB, voffB); PG8_STAGEX(rsA, PG8_SA(0, 0), a2, voffA);
;             PG8_WAIT_V(8); PG8_WAIT_L(0); PG8_BAR; PG8_MMA(1, 0, At, B0); PG8_MMA(1, 1, At, B1); PG8_BAR; PG8_SCHED;
.LBB0_1377:
	v_add_u32_e32 v142, 0x10000, v185
	v_add_u32_e32 v158, 0x14000, v185
	ds_read_b128 v[130:133], v142
	ds_read_b128 v[134:137], v142 offset:1024
	ds_read_b128 v[138:141], v142 offset:2048
	ds_read_b128 v[142:145], v142 offset:3072
	ds_read_b128 v[146:149], v158
	ds_read_b128 v[150:153], v158 offset:1024
	ds_read_b128 v[154:157], v158 offset:2048
	ds_read_b128 v[158:161], v158 offset:3072
	s_add_i32 s50, s43, 0xfff40080
	s_cmp_eq_u32 s60, 12
	s_cselect_b32 s63, s30, s50
	s_cselect_b32 s62, s31, s59
	s_add_i32 s61, s63, 0x80
	s_mov_b32 m0, s23
	ds_read_b128 v[162:165], v186
	ds_read_b128 v[166:169], v186 offset:1024
	ds_read_b128 v[190:193], v186 offset:2048
	ds_read_b128 v[194:197], v186 offset:3072
	ds_read_b128 v[198:201], v186 offset:4096
	ds_read_b128 v[202:205], v186 offset:5120
	ds_read_b128 v[206:209], v186 offset:6144
	ds_read_b128 v[210:213], v186 offset:7168
	buffer_load_dwordx4 v173, s[76:79], s43 offen lds
	s_mov_b32 m0, s24
	s_nop 0
	buffer_load_dwordx4 v178, s[76:79], s43 offen lds
	s_waitcnt vmcnt(8)
	s_waitcnt lgkmcnt(0)
	s_setprio 1
	s_barrier
	v_mfma_f32_16x16x32_bf16 v[126:129], v[130:133], v[162:165], v[126:129]
	v_mfma_f32_16x16x32_bf16 v[126:129], v[134:137], v[166:169], v[126:129]
	v_mfma_f32_16x16x32_bf16 v[122:125], v[138:141], v[162:165], v[122:125]
	v_mfma_f32_16x16x32_bf16 v[122:125], v[142:145], v[166:169], v[122:125]
	v_mfma_f32_16x16x32_bf16 v[114:117], v[138:141], v[190:193], v[114:117]
	v_mfma_f32_16x16x32_bf16 v[114:117], v[142:145], v[194:197], v[114:117]
	v_mfma_f32_16x16x32_bf16 v[118:121], v[130:133], v[190:193], v[118:121]
	v_mfma_f32_16x16x32_bf16 v[118:121], v[134:137], v[194:197], v[118:121]
	v_mfma_f32_16x16x32_bf16 v[110:113], v[130:133], v[198:201], v[110:113]
	v_mfma_f32_16x16x32_bf16 v[110:113], v[134:137], v[202:205], v[110:113]
	v_mfma_f32_16x16x32_bf16 v[106:109], v[138:141], v[198:201], v[106:109]
	v_mfma_f32_16x16x32_bf16 v[106:109], v[142:145], v[202:205], v[106:109]
	v_mfma_f32_16x16x32_bf16 v[98:101], v[138:141], v[206:209], v[98:101]
	v_mfma_f32_16x16x32_bf16 v[98:101], v[142:145], v[210:213], v[98:101]
	v_mfma_f32_16x16x32_bf16 v[102:105], v[130:133], v[206:209], v[102:105]
	v_mfma_f32_16x16x32_bf16 v[102:105], v[134:137], v[210:213], v[102:105]
	v_mfma_f32_16x16x32_bf16 v[94:97], v[146:149], v[162:165], v[94:97]
	v_mfma_f32_16x16x32_bf16 v[94:97], v[150:153], v[166:169], v[94:97]
	v_mfma_f32_16x16x32_bf16 v[90:93], v[154:157], v[162:165], v[90:93]
	v_mfma_f32_16x16x32_bf16 v[90:93], v[158:161], v[166:169], v[90:93]
	v_mfma_f32_16x16x32_bf16 v[82:85], v[154:157], v[190:193], v[82:85]
	v_mfma_f32_16x16x32_bf16 v[82:85], v[158:161], v[194:197], v[82:85]
	v_mfma_f32_16x16x32_bf16 v[86:89], v[146:149], v[190:193], v[86:89]
	v_mfma_f32_16x16x32_bf16 v[86:89], v[150:153], v[194:197], v[86:89]
	v_mfma_f32_16x16x32_bf16 v[78:81], v[146:149], v[198:201], v[78:81]
	v_mfma_f32_16x16x32_bf16 v[78:81], v[150:153], v[202:205], v[78:81]
	v_mfma_f32_16x16x32_bf16 v[74:77], v[154:157], v[198:201], v[74:77]
	v_mfma_f32_16x16x32_bf16 v[74:77], v[158:161], v[202:205], v[74:77]
	v_mfma_f32_16x16x32_bf16 v[66:69], v[154:157], v[206:209], v[66:69]
	v_mfma_f32_16x16x32_bf16 v[66:69], v[158:161], v[210:213], v[66:69]
	v_mfma_f32_16x16x32_bf16 v[70:73], v[146:149], v[206:209], v[70:73]
	v_mfma_f32_16x16x32_bf16 v[70:73], v[150:153], v[210:213], v[70:73]
	s_barrier
	s_setprio 0
	s_mov_b32 m0, s7
	s_mov_b32 s50, s78
	s_mov_b32 s51, s79
	ds_read_b128 v[162:165], v186 offset:16384
	ds_read_b128 v[166:169], v186 offset:17408
	ds_read_b128 v[190:193], v186 offset:18432
	ds_read_b128 v[194:197], v186 offset:19456
	ds_read_b128 v[198:201], v186 offset:20480
	ds_read_b128 v[202:205], v186 offset:21504
	ds_read_b128 v[206:209], v186 offset:22528
	ds_read_b128 v[210:213], v186 offset:23552
	buffer_load_dwordx4 v177, s[48:51], s62 offen lds
	s_mov_b32 m0, s11
	s_add_i32 s64, s62, 0x40000
	buffer_load_dwordx4 v179, s[48:51], s62 offen lds
	s_mov_b32 m0, s12
	s_nop 0
	buffer_load_dwordx4 v177, s[48:51], s64 offen lds
	s_mov_b32 m0, s13
	s_nop 0
	buffer_load_dwordx4 v179, s[48:51], s64 offen lds
	s_mov_b32 m0, s5
	s_nop 0
	buffer_load_dwordx4 v173, s[76:79], s63 offen lds
	s_mov_b32 m0, s14
	s_nop 0
	buffer_load_dwordx4 v178, s[76:79], s63 offen lds
	s_waitcnt vmcnt(8)
	s_waitcnt lgkmcnt(0)
	s_setprio 1
	s_barrier
	v_mfma_f32_16x16x32_bf16 v[62:65], v[130:133], v[162:165], v[62:65]
	v_mfma_f32_16x16x32_bf16 v[62:65], v[134:137], v[166:169], v[62:65]
	v_mfma_f32_16x16x32_bf16 v[58:61], v[138:141], v[162:165], v[58:61]
	v_mfma_f32_16x16x32_bf16 v[58:61], v[142:145], v[166:169], v[58:61]
	v_mfma_f32_16x16x32_bf16 v[50:53], v[138:141], v[190:193], v[50:53]
	v_mfma_f32_16x16x32_bf16 v[50:53], v[142:145], v[194:197], v[50:53]
	v_mfma_f32_16x16x32_bf16 v[54:57], v[130:133], v[190:193], v[54:57]
	v_mfma_f32_16x16x32_bf16 v[54:57], v[134:137], v[194:197], v[54:57]
	v_mfma_f32_16x16x32_bf16 v[46:49], v[130:133], v[198:201], v[46:49]
	v_mfma_f32_16x16x32_bf16 v[46:49], v[134:137], v[202:205], v[46:49]
	v_mfma_f32_16x16x32_bf16 v[42:45], v[138:141], v[198:201], v[42:45]
	v_mfma_f32_16x16x32_bf16 v[42:45], v[142:145], v[202:205], v[42:45]
	v_mfma_f32_16x16x32_bf16 v[34:37], v[138:141], v[206:209], v[34:37]
	v_mfma_f32_16x16x32_bf16 v[34:37], v[142:145], v[210:213], v[34:37]
	v_mfma_f32_16x16x32_bf16 v[38:41], v[130:133], v[206:209], v[38:41]
	v_mfma_f32_16x16x32_bf16 v[38:41], v[134:137], v[210:213], v[38:41]
	v_mfma_f32_16x16x32_bf16 v[30:33], v[146:149], v[162:165], v[30:33]
	v_mfma_f32_16x16x32_bf16 v[30:33], v[150:153], v[166:169], v[30:33]
	v_mfma_f32_16x16x32_bf16 v[26:29], v[154:157], v[162:165], v[26:29]
	v_mfma_f32_16x16x32_bf16 v[26:29], v[158:161], v[166:169], v[26:29]
	v_mfma_f32_16x16x32_bf16 v[18:21], v[154:157], v[190:193], v[18:21]
	v_mfma_f32_16x16x32_bf16 v[18:21], v[158:161], v[194:197], v[18:21]
	v_mfma_f32_16x16x32_bf16 v[22:25], v[146:149], v[190:193], v[22:25]
	v_mfma_f32_16x16x32_bf16 v[22:25], v[150:153], v[194:197], v[22:25]
	v_mfma_f32_16x16x32_bf16 v[14:17], v[146:149], v[198:201], v[14:17]
	v_mfma_f32_16x16x32_bf16 v[14:17], v[150:153], v[202:205], v[14:17]
	v_mfma_f32_16x16x32_bf16 v[10:13], v[154:157], v[198:201], v[10:13]
	v_mfma_f32_16x16x32_bf16 v[10:13], v[158:161], v[202:205], v[10:13]
	v_mfma_f32_16x16x32_bf16 v[2:5], v[154:157], v[206:209], v[2:5]
	v_mfma_f32_16x16x32_bf16 v[2:5], v[158:161], v[210:213], v[2:5]
	v_mfma_f32_16x16x32_bf16 v[6:9], v[146:149], v[206:209], v[6:9]
	v_mfma_f32_16x16x32_bf16 v[6:9], v[150:153], v[210:213], v[6:9]
	s_barrier
; #define PG8_STAGEX(rs, bufoff, soff, voff) do { _Pragma("unroll") for (int _i = 0; _i < 2; ++_i) \
;         __builtin_amdgcn_raw_ptr_buffer_load_lds(rs, (LAS unsigned*)(lds + (bufoff) + ldsw + _i * 8192), 16, (voff)[_i], (soff), 0, 0); } while (0)
; #define PG8_LDA(dst, b, h) do { _Pragma("unroll") for (int m = 0; m < 4; ++m) _Pragma("unroll") for (int k = 0; k < 2; ++k) dst[m][k] = *(const LAS bf16x8*)(lds + PG8_SA(b, h) + aoff + m * 2048 + k * 1024); } while (0)
; #define PG8_LDB(dst, b, h) do { _Pragma("unroll") for (int n = 0; n < 2; ++n) _Pragma("unroll") for (int k = 0; k < 2; ++k) dst[n][k] = *(const LAS bf16x8*)(lds + PG8_SB(b, h) + boff + n * 2048 + k * 1024); } while (0)
; #define PG8_WAIT_V(n) asm volatile("s_waitcnt vmcnt(" #n ")" ::: "memory")
; #define PG8_WAIT_L(n) asm volatile("s_waitcnt lgkmcnt(" #n ")" ::: "memory")
; #define PG8_BAR __builtin_amdgcn_s_barrier()
; #define PG8_SCHED __builtin_amdgcn_sched_barrier(0)
;     ...
;             PG8_LDA(At, 0, 1); PG8_STAGEX(rsB, PG8_SB(0, 0), b2, voffB); PG8_STAGEX(rsB, PG8_SB(0, 1), b2 + hstepB, voffB); PG8_STAGEX(rsA, PG8_SA(0, 0), a2, voffA);
;             PG8_WAIT_V(8); PG8_WAIT_L(0); PG8_BAR; PG8_MMA(1, 0, At, B0); PG8_MMA(1, 1, At, B1); PG8_BAR; PG8_SCHED;
;             PG8_LDB(B0, 1, 0); PG8_LDB(B1, 1, 1); PG8_SCHED; PG8_LDA(At, 1, 0); PG8_STAGEX(rsA, PG8_SA(0, 1), a2 + hstepA, voffA);
;             PG8_WAIT_V(8); PG8_WAIT_L(0); PG8_BAR; PG8_MMA(0, 0, At, B0); PG8_MMA(0, 1, At, B1); PG8_BAR; PG8_SCHED;
;             PG8_LDA(At, 1, 1); PG8_STAGEX(rsB, PG8_SB(1, 0), b3, voffB); PG8_STAGEX(rsB, PG8_SB(1, 1), b3 + hstepB, voffB); PG8_STAGEX(rsA, PG8_SA(1, 0), a3, voffA);
;             PG8_WAIT_V(8); PG8_WAIT_L(0); PG8_BAR; PG8_MMA(1, 0, At, B0); PG8_MMA(1, 1, At, B1); PG8_BAR; PG8_SCHED;
;         }
;     ...
;         if (wr == 0) PG8_BAR;
	s_setprio 0
	v_add_u32_e32 v142, 0x18000, v185
	v_add_u32_e32 v158, 0x1c000, v185
	ds_read_b128 v[130:133], v142
	ds_read_b128 v[134:137], v142 offset:1024
	ds_read_b128 v[138:141], v142 offset:2048
	ds_read_b128 v[142:145], v142 offset:3072
	ds_read_b128 v[146:149], v158
	ds_read_b128 v[150:153], v158 offset:1024
	ds_read_b128 v[154:157], v158 offset:2048
	ds_read_b128 v[158:161], v158 offset:3072
	s_add_i32 s63, s63, 0xc0000
	s_mov_b32 m0, s15
	ds_read_b128 v[162:165], v186 offset:32768
	ds_read_b128 v[166:169], v186 offset:33792
	ds_read_b128 v[190:193], v186 offset:34816
	ds_read_b128 v[194:197], v186 offset:35840
	ds_read_b128 v[198:201], v186 offset:36864
	ds_read_b128 v[202:205], v186 offset:37888
	ds_read_b128 v[206:209], v186 offset:38912
	ds_read_b128 v[210:213], v186 offset:39936
	buffer_load_dwordx4 v173, s[76:79], s63 offen lds
	s_mov_b32 m0, s16
	s_nop 0
	buffer_load_dwordx4 v178, s[76:79], s63 offen lds
	s_waitcnt vmcnt(8)
	s_waitcnt lgkmcnt(0)
	s_setprio 1
	s_barrier
	v_mfma_f32_16x16x32_bf16 v[126:129], v[130:133], v[162:165], v[126:129]
	v_mfma_f32_16x16x32_bf16 v[126:129], v[134:137], v[166:169], v[126:129]
	v_mfma_f32_16x16x32_bf16 v[122:125], v[138:141], v[162:165], v[122:125]
	v_mfma_f32_16x16x32_bf16 v[122:125], v[142:145], v[166:169], v[122:125]
	v_mfma_f32_16x16x32_bf16 v[114:117], v[138:141], v[190:193], v[114:117]
	v_mfma_f32_16x16x32_bf16 v[114:117], v[142:145], v[194:197], v[114:117]
	v_mfma_f32_16x16x32_bf16 v[118:121], v[130:133], v[190:193], v[118:121]
	v_mfma_f32_16x16x32_bf16 v[118:121], v[134:137], v[194:197], v[118:121]
	v_mfma_f32_16x16x32_bf16 v[110:113], v[130:133], v[198:201], v[110:113]
	v_mfma_f32_16x16x32_bf16 v[110:113], v[134:137], v[202:205], v[110:113]
	v_mfma_f32_16x16x32_bf16 v[106:109], v[138:141], v[198:201], v[106:109]
	v_mfma_f32_16x16x32_bf16 v[106:109], v[142:145], v[202:205], v[106:109]
	v_mfma_f32_16x16x32_bf16 v[98:101], v[138:141], v[206:209], v[98:101]
	v_mfma_f32_16x16x32_bf16 v[98:101], v[142:145], v[210:213], v[98:101]
	v_mfma_f32_16x16x32_bf16 v[102:105], v[130:133], v[206:209], v[102:105]
	v_mfma_f32_16x16x32_bf16 v[102:105], v[134:137], v[210:213], v[102:105]
	v_mfma_f32_16x16x32_bf16 v[94:97], v[146:149], v[162:165], v[94:97]
	v_mfma_f32_16x16x32_bf16 v[94:97], v[150:153], v[166:169], v[94:97]
	v_mfma_f32_16x16x32_bf16 v[90:93], v[154:157], v[162:165], v[90:93]
	v_mfma_f32_16x16x32_bf16 v[90:93], v[158:161], v[166:169], v[90:93]
	v_mfma_f32_16x16x32_bf16 v[82:85], v[154:157], v[190:193], v[82:85]
	v_mfma_f32_16x16x32_bf16 v[82:85], v[158:161], v[194:197], v[82:85]
	v_mfma_f32_16x16x32_bf16 v[86:89], v[146:149], v[190:193], v[86:89]
	v_mfma_f32_16x16x32_bf16 v[86:89], v[150:153], v[194:197], v[86:89]
	v_mfma_f32_16x16x32_bf16 v[78:81], v[146:149], v[198:201], v[78:81]
	v_mfma_f32_16x16x32_bf16 v[78:81], v[150:153], v[202:205], v[78:81]
	v_mfma_f32_16x16x32_bf16 v[74:77], v[154:157], v[198:201], v[74:77]
	v_mfma_f32_16x16x32_bf16 v[74:77], v[158:161], v[202:205], v[74:77]
	v_mfma_f32_16x16x32_bf16 v[66:69], v[154:157], v[206:209], v[66:69]
	v_mfma_f32_16x16x32_bf16 v[66:69], v[158:161], v[210:213], v[66:69]
	v_mfma_f32_16x16x32_bf16 v[70:73], v[146:149], v[206:209], v[70:73]
	v_mfma_f32_16x16x32_bf16 v[70:73], v[150:153], v[210:213], v[70:73]
	s_barrier
	s_setprio 0
	s_mov_b32 m0, s17
	s_add_i32 s63, s62, 0x80
	ds_read_b128 v[162:165], v186 offset:49152
	ds_read_b128 v[166:169], v186 offset:50176
	ds_read_b128 v[190:193], v186 offset:51200
	ds_read_b128 v[194:197], v186 offset:52224
	ds_read_b128 v[198:201], v186 offset:53248
	ds_read_b128 v[202:205], v186 offset:54272
	ds_read_b128 v[206:209], v186 offset:55296
	ds_read_b128 v[210:213], v186 offset:56320
	buffer_load_dwordx4 v177, s[48:51], s63 offen lds
	s_mov_b32 m0, s18
	s_add_i32 s62, s62, 0x40080
	buffer_load_dwordx4 v179, s[48:51], s63 offen lds
	s_mov_b32 m0, s21
	s_nop 0
	buffer_load_dwordx4 v177, s[48:51], s62 offen lds
	s_mov_b32 m0, s22
	s_nop 0
	buffer_load_dwordx4 v179, s[48:51], s62 offen lds
	s_mov_b32 m0, s19
	s_cmp_eq_u32 s60, 12
	buffer_load_dwordx4 v173, s[76:79], s61 offen lds
	s_mov_b32 m0, s20
	s_cselect_b64 vcc, s[46:47], 0
	buffer_load_dwordx4 v178, s[76:79], s61 offen lds
	s_waitcnt vmcnt(8)
	s_waitcnt lgkmcnt(0)
	s_setprio 1
	s_barrier
	v_mfma_f32_16x16x32_bf16 v[62:65], v[130:133], v[162:165], v[62:65]
	v_mfma_f32_16x16x32_bf16 v[62:65], v[134:137], v[166:169], v[62:65]
	v_mfma_f32_16x16x32_bf16 v[58:61], v[138:141], v[162:165], v[58:61]
	v_mfma_f32_16x16x32_bf16 v[58:61], v[142:145], v[166:169], v[58:61]
	v_mfma_f32_16x16x32_bf16 v[50:53], v[138:141], v[190:193], v[50:53]
	v_mfma_f32_16x16x32_bf16 v[50:53], v[142:145], v[194:197], v[50:53]
	v_mfma_f32_16x16x32_bf16 v[54:57], v[130:133], v[190:193], v[54:57]
	v_mfma_f32_16x16x32_bf16 v[54:57], v[134:137], v[194:197], v[54:57]
	v_mfma_f32_16x16x32_bf16 v[46:49], v[130:133], v[198:201], v[46:49]
	v_mfma_f32_16x16x32_bf16 v[46:49], v[134:137], v[202:205], v[46:49]
	v_mfma_f32_16x16x32_bf16 v[42:45], v[138:141], v[198:201], v[42:45]
	v_mfma_f32_16x16x32_bf16 v[42:45], v[142:145], v[202:205], v[42:45]
	v_mfma_f32_16x16x32_bf16 v[34:37], v[138:141], v[206:209], v[34:37]
	v_mfma_f32_16x16x32_bf16 v[34:37], v[142:145], v[210:213], v[34:37]
	v_mfma_f32_16x16x32_bf16 v[38:41], v[130:133], v[206:209], v[38:41]
	v_mfma_f32_16x16x32_bf16 v[38:41], v[134:137], v[210:213], v[38:41]
	v_mfma_f32_16x16x32_bf16 v[30:33], v[146:149], v[162:165], v[30:33]
	v_mfma_f32_16x16x32_bf16 v[30:33], v[150:153], v[166:169], v[30:33]
	v_mfma_f32_16x16x32_bf16 v[26:29], v[154:157], v[162:165], v[26:29]
	v_mfma_f32_16x16x32_bf16 v[26:29], v[158:161], v[166:169], v[26:29]
	v_mfma_f32_16x16x32_bf16 v[18:21], v[154:157], v[190:193], v[18:21]
	v_mfma_f32_16x16x32_bf16 v[18:21], v[158:161], v[194:197], v[18:21]
	v_mfma_f32_16x16x32_bf16 v[22:25], v[146:149], v[190:193], v[22:25]
	v_mfma_f32_16x16x32_bf16 v[22:25], v[150:153], v[194:197], v[22:25]
	v_mfma_f32_16x16x32_bf16 v[14:17], v[146:149], v[198:201], v[14:17]
	v_mfma_f32_16x16x32_bf16 v[14:17], v[150:153], v[202:205], v[14:17]
	v_mfma_f32_16x16x32_bf16 v[10:13], v[154:157], v[198:201], v[10:13]
	v_mfma_f32_16x16x32_bf16 v[10:13], v[158:161], v[202:205], v[10:13]
	v_mfma_f32_16x16x32_bf16 v[2:5], v[154:157], v[206:209], v[2:5]
	v_mfma_f32_16x16x32_bf16 v[2:5], v[158:161], v[210:213], v[2:5]
	v_mfma_f32_16x16x32_bf16 v[6:9], v[146:149], v[206:209], v[6:9]
	v_mfma_f32_16x16x32_bf16 v[6:9], v[150:153], v[210:213], v[6:9]
	s_cbranch_vccnz .Lee_skip_1377
	s_barrier
.Lee_skip_1377:
	s_setprio 0
	s_add_i32 s60, s60, 2
	s_addk_i32 s43, 0x100
	s_addk_i32 s59, 0x100
	s_cmp_gt_u32 s60, 13
	s_cbranch_scc0 .LBB0_1377

; #define PG8_STAGEX(rs, bufoff, soff, voff) do { _Pragma("unroll") for (int _i = 0; _i < 2; ++_i) \
;         __builtin_amdgcn_raw_ptr_buffer_load_lds(rs, (LAS unsigned*)(lds + (bufoff) + ldsw + _i * 8192), 16, (voff)[_i], (soff), 0, 0); } while (0)
; #define PG8_LDA(dst, b, h) do { _Pragma("unroll") for (int m = 0; m < 4; ++m) _Pragma("unroll") for (int k = 0; k < 2; ++k) dst[m][k] = *(const LAS bf16x8*)(lds + PG8_SA(b, h) + aoff + m * 2048 + k * 1024); } while (0)
; #define PG8_LDB(dst, b, h) do { _Pragma("unroll") for (int n = 0; n < 2; ++n) _Pragma("unroll") for (int k = 0; k < 2; ++k) dst[n][k] = *(const LAS bf16x8*)(lds + PG8_SB(b, h) + boff + n * 2048 + k * 1024); } while (0)
; #define PG8_WAIT_V(n) asm volatile("s_waitcnt vmcnt(" #n ")" ::: "memory")
; #define PG8_WAIT_L(n) asm volatile("s_waitcnt lgkmcnt(" #n ")" ::: "memory")
; #define PG8_BAR __builtin_amdgcn_s_barrier()
; #define PG8_SCHED __builtin_amdgcn_sched_barrier(0)
;     ...
;             const unsigned a1 = cA + (unsigned)(t + 1) * kstep;
;             const unsigned a2 = last ? nA : cA + (unsigned)(t + 2) * kstep, b2 = last ? nB : cB + (unsigned)(t + 2) * kstep;
;             const unsigned a3 = a2 + kstep, b3 = b2 + kstep;
;             PG8_LDB(B0, 0, 0); PG8_LDB(B1, 0, 1); PG8_SCHED; PG8_LDA(At, 0, 0); PG8_STAGEX(rsA, PG8_SA(1, 1), a1 + hstepA, voffA);
;             PG8_WAIT_V(8); PG8_WAIT_L(0); PG8_BAR; PG8_MMA(0, 0, At, B0); PG8_MMA(0, 1, At, B1); PG8_BAR; PG8_SCHED;
;             PG8_LDA(At, 0, 1); PG8_STAGEX(rsB, PG8_SB(0, 0), b2, voffB); PG8_STAGEX(rsB, PG8_SB(0, 1), b2 + hstepB, voffB); PG8_STAGEX(rsA, PG8_SA(0, 0), a2, voffA);
;             PG8_WAIT_V(8); PG8_WAIT_L(0); PG8_BAR; PG8_MMA(1, 0, At, B0); PG8_MMA(1, 1, At, B1); PG8_BAR; PG8_SCHED;
.LBB0_1529:
	v_add_u32_e32 v118, 0x10000, v210
	v_add_u32_e32 v142, 0x14000, v210
	ds_read_b128 v[106:109], v118
	ds_read_b128 v[110:113], v118 offset:1024
	ds_read_b128 v[114:117], v118 offset:2048
	ds_read_b128 v[118:121], v118 offset:3072
	ds_read_b128 v[122:125], v142
	ds_read_b128 v[126:129], v142 offset:1024
	ds_read_b128 v[130:133], v142 offset:2048
	ds_read_b128 v[142:145], v142 offset:3072
	s_add_i32 s46, s59, 0xfff80080
	s_cmp_eq_u32 s64, 28
	s_cselect_b32 s67, s30, s46
	s_cselect_b32 s66, s31, s63
	s_or_b32 s65, s67, 0x80
	s_mov_b32 m0, s76
	ds_read_b128 v[164:167], v211
	ds_read_b128 v[168:171], v211 offset:1024
	ds_read_b128 v[182:185], v211 offset:2048
	ds_read_b128 v[186:189], v211 offset:3072
	ds_read_b128 v[190:193], v211 offset:4096
	ds_read_b128 v[194:197], v211 offset:5120
	ds_read_b128 v[198:201], v211 offset:6144
	ds_read_b128 v[202:205], v211 offset:7168
	buffer_load_dwordx4 v178, s[40:43], s59 offen lds
	s_mov_b32 m0, s77
	s_nop 0
	buffer_load_dwordx4 v206, s[40:43], s59 offen lds
	s_waitcnt vmcnt(8)
	s_waitcnt lgkmcnt(0)
	s_setprio 1
	s_barrier
	v_mfma_f32_16x16x32_bf16 v[158:161], v[106:109], v[164:167], v[158:161]
	v_mfma_f32_16x16x32_bf16 v[158:161], v[110:113], v[168:171], v[158:161]
	v_mfma_f32_16x16x32_bf16 v[154:157], v[114:117], v[164:167], v[154:157]
	v_mfma_f32_16x16x32_bf16 v[154:157], v[118:121], v[168:171], v[154:157]
	v_mfma_f32_16x16x32_bf16 v[146:149], v[114:117], v[182:185], v[146:149]
	v_mfma_f32_16x16x32_bf16 v[146:149], v[118:121], v[186:189], v[146:149]
	v_mfma_f32_16x16x32_bf16 v[150:153], v[106:109], v[182:185], v[150:153]
	v_mfma_f32_16x16x32_bf16 v[150:153], v[110:113], v[186:189], v[150:153]
	v_mfma_f32_16x16x32_bf16 v[138:141], v[106:109], v[190:193], v[138:141]
	v_mfma_f32_16x16x32_bf16 v[138:141], v[110:113], v[194:197], v[138:141]
	v_mfma_f32_16x16x32_bf16 v[134:137], v[114:117], v[190:193], v[134:137]
	v_mfma_f32_16x16x32_bf16 v[134:137], v[118:121], v[194:197], v[134:137]
	v_mfma_f32_16x16x32_bf16 v[98:101], v[114:117], v[198:201], v[98:101]
	v_mfma_f32_16x16x32_bf16 v[98:101], v[118:121], v[202:205], v[98:101]
	v_mfma_f32_16x16x32_bf16 v[102:105], v[106:109], v[198:201], v[102:105]
	v_mfma_f32_16x16x32_bf16 v[102:105], v[110:113], v[202:205], v[102:105]
	v_mfma_f32_16x16x32_bf16 v[62:65], v[122:125], v[164:167], v[62:65]
	v_mfma_f32_16x16x32_bf16 v[62:65], v[126:129], v[168:171], v[62:65]
	v_mfma_f32_16x16x32_bf16 v[58:61], v[130:133], v[164:167], v[58:61]
	v_mfma_f32_16x16x32_bf16 v[58:61], v[142:145], v[168:171], v[58:61]
	v_mfma_f32_16x16x32_bf16 v[50:53], v[130:133], v[182:185], v[50:53]
	v_mfma_f32_16x16x32_bf16 v[50:53], v[142:145], v[186:189], v[50:53]
	v_mfma_f32_16x16x32_bf16 v[54:57], v[122:125], v[182:185], v[54:57]
	v_mfma_f32_16x16x32_bf16 v[54:57], v[126:129], v[186:189], v[54:57]
	v_mfma_f32_16x16x32_bf16 v[46:49], v[122:125], v[190:193], v[46:49]
	v_mfma_f32_16x16x32_bf16 v[46:49], v[126:129], v[194:197], v[46:49]
	v_mfma_f32_16x16x32_bf16 v[42:45], v[130:133], v[190:193], v[42:45]
	v_mfma_f32_16x16x32_bf16 v[42:45], v[142:145], v[194:197], v[42:45]
	v_mfma_f32_16x16x32_bf16 v[34:37], v[130:133], v[198:201], v[34:37]
	v_mfma_f32_16x16x32_bf16 v[34:37], v[142:145], v[202:205], v[34:37]
	v_mfma_f32_16x16x32_bf16 v[38:41], v[122:125], v[198:201], v[38:41]
	v_mfma_f32_16x16x32_bf16 v[38:41], v[126:129], v[202:205], v[38:41]
	s_barrier
	s_setprio 0
	s_mov_b32 m0, s17
	s_mov_b32 s46, s42
	s_mov_b32 s47, s43
	ds_read_b128 v[164:167], v211 offset:16384
	ds_read_b128 v[168:171], v211 offset:17408
	ds_read_b128 v[182:185], v211 offset:18432
	ds_read_b128 v[186:189], v211 offset:19456
	ds_read_b128 v[190:193], v211 offset:20480
	ds_read_b128 v[194:197], v211 offset:21504
	ds_read_b128 v[198:201], v211 offset:22528
	ds_read_b128 v[202:205], v211 offset:23552
	buffer_load_dwordx4 v179, s[44:47], s66 offen lds
	s_mov_b32 m0, s18
	s_add_i32 s68, s66, 0x80000
	buffer_load_dwordx4 v207, s[44:47], s66 offen lds
	s_mov_b32 m0, s19
	s_nop 0
	buffer_load_dwordx4 v179, s[44:47], s68 offen lds
	s_mov_b32 m0, s20
	s_nop 0
	buffer_load_dwordx4 v207, s[44:47], s68 offen lds
	s_mov_b32 m0, s16
	s_nop 0
	buffer_load_dwordx4 v178, s[40:43], s67 offen lds
	s_mov_b32 m0, s21
	s_nop 0
	buffer_load_dwordx4 v206, s[40:43], s67 offen lds
	s_waitcnt vmcnt(8)
	s_waitcnt lgkmcnt(0)
	s_setprio 1
	s_barrier
	v_mfma_f32_16x16x32_bf16 v[94:97], v[106:109], v[164:167], v[94:97]
	v_mfma_f32_16x16x32_bf16 v[94:97], v[110:113], v[168:171], v[94:97]
	v_mfma_f32_16x16x32_bf16 v[90:93], v[114:117], v[164:167], v[90:93]
	v_mfma_f32_16x16x32_bf16 v[90:93], v[118:121], v[168:171], v[90:93]
	v_mfma_f32_16x16x32_bf16 v[82:85], v[114:117], v[182:185], v[82:85]
	v_mfma_f32_16x16x32_bf16 v[82:85], v[118:121], v[186:189], v[82:85]
	v_mfma_f32_16x16x32_bf16 v[86:89], v[106:109], v[182:185], v[86:89]
	v_mfma_f32_16x16x32_bf16 v[86:89], v[110:113], v[186:189], v[86:89]
	v_mfma_f32_16x16x32_bf16 v[78:81], v[106:109], v[190:193], v[78:81]
	v_mfma_f32_16x16x32_bf16 v[78:81], v[110:113], v[194:197], v[78:81]
	v_mfma_f32_16x16x32_bf16 v[74:77], v[114:117], v[190:193], v[74:77]
	v_mfma_f32_16x16x32_bf16 v[74:77], v[118:121], v[194:197], v[74:77]
	v_mfma_f32_16x16x32_bf16 v[66:69], v[114:117], v[198:201], v[66:69]
	v_mfma_f32_16x16x32_bf16 v[66:69], v[118:121], v[202:205], v[66:69]
	v_mfma_f32_16x16x32_bf16 v[70:73], v[106:109], v[198:201], v[70:73]
	v_mfma_f32_16x16x32_bf16 v[70:73], v[110:113], v[202:205], v[70:73]
	v_mfma_f32_16x16x32_bf16 v[30:33], v[122:125], v[164:167], v[30:33]
	v_mfma_f32_16x16x32_bf16 v[30:33], v[126:129], v[168:171], v[30:33]
	v_mfma_f32_16x16x32_bf16 v[26:29], v[130:133], v[164:167], v[26:29]
	v_mfma_f32_16x16x32_bf16 v[26:29], v[142:145], v[168:171], v[26:29]
	v_mfma_f32_16x16x32_bf16 v[18:21], v[130:133], v[182:185], v[18:21]
	v_mfma_f32_16x16x32_bf16 v[18:21], v[142:145], v[186:189], v[18:21]
	v_mfma_f32_16x16x32_bf16 v[22:25], v[122:125], v[182:185], v[22:25]
	v_mfma_f32_16x16x32_bf16 v[22:25], v[126:129], v[186:189], v[22:25]
	v_mfma_f32_16x16x32_bf16 v[14:17], v[122:125], v[190:193], v[14:17]
	v_mfma_f32_16x16x32_bf16 v[14:17], v[126:129], v[194:197], v[14:17]
	v_mfma_f32_16x16x32_bf16 v[10:13], v[130:133], v[190:193], v[10:13]
	v_mfma_f32_16x16x32_bf16 v[10:13], v[142:145], v[194:197], v[10:13]
	v_mfma_f32_16x16x32_bf16 v[2:5], v[130:133], v[198:201], v[2:5]
	v_mfma_f32_16x16x32_bf16 v[2:5], v[142:145], v[202:205], v[2:5]
	v_mfma_f32_16x16x32_bf16 v[6:9], v[122:125], v[198:201], v[6:9]
	v_mfma_f32_16x16x32_bf16 v[6:9], v[126:129], v[202:205], v[6:9]
	s_barrier
; #define PG8_STAGEX(rs, bufoff, soff, voff) do { _Pragma("unroll") for (int _i = 0; _i < 2; ++_i) \
;         __builtin_amdgcn_raw_ptr_buffer_load_lds(rs, (LAS unsigned*)(lds + (bufoff) + ldsw + _i * 8192), 16, (voff)[_i], (soff), 0, 0); } while (0)
; #define PG8_LDA(dst, b, h) do { _Pragma("unroll") for (int m = 0; m < 4; ++m) _Pragma("unroll") for (int k = 0; k < 2; ++k) dst[m][k] = *(const LAS bf16x8*)(lds + PG8_SA(b, h) + aoff + m * 2048 + k * 1024); } while (0)
; #define PG8_LDB(dst, b, h) do { _Pragma("unroll") for (int n = 0; n < 2; ++n) _Pragma("unroll") for (int k = 0; k < 2; ++k) dst[n][k] = *(const LAS bf16x8*)(lds + PG8_SB(b, h) + boff + n * 2048 + k * 1024); } while (0)
; #define PG8_WAIT_V(n) asm volatile("s_waitcnt vmcnt(" #n ")" ::: "memory")
; #define PG8_WAIT_L(n) asm volatile("s_waitcnt lgkmcnt(" #n ")" ::: "memory")
; #define PG8_BAR __builtin_amdgcn_s_barrier()
; #define PG8_SCHED __builtin_amdgcn_sched_barrier(0)
;     ...
;             PG8_LDB(B0, 1, 0); PG8_LDB(B1, 1, 1); PG8_SCHED; PG8_LDA(At, 1, 0); PG8_STAGEX(rsA, PG8_SA(0, 1), a2 + hstepA, voffA);
;             PG8_WAIT_V(8); PG8_WAIT_L(0); PG8_BAR; PG8_MMA(0, 0, At, B0); PG8_MMA(0, 1, At, B1); PG8_BAR; PG8_SCHED;
;             PG8_LDA(At, 1, 1); PG8_STAGEX(rsB, PG8_SB(1, 0), b3, voffB); PG8_STAGEX(rsB, PG8_SB(1, 1), b3 + hstepB, voffB); PG8_STAGEX(rsA, PG8_SA(1, 0), a3, voffA);
;             PG8_WAIT_V(8); PG8_WAIT_L(0); PG8_BAR; PG8_MMA(1, 0, At, B0); PG8_MMA(1, 1, At, B1); PG8_BAR; PG8_SCHED;
;         }
;     ...
;         if (wr == 0) PG8_BAR;
	s_setprio 0
	v_add_u32_e32 v118, 0x18000, v210
	v_add_u32_e32 v142, 0x1c000, v210
	ds_read_b128 v[106:109], v118
	ds_read_b128 v[110:113], v118 offset:1024
	ds_read_b128 v[114:117], v118 offset:2048
	ds_read_b128 v[118:121], v118 offset:3072
	ds_read_b128 v[122:125], v142
	ds_read_b128 v[126:129], v142 offset:1024
	ds_read_b128 v[130:133], v142 offset:2048
	ds_read_b128 v[142:145], v142 offset:3072
	s_add_i32 s67, s67, 0x80000
	s_mov_b32 m0, s22
	ds_read_b128 v[164:167], v211 offset:32768
	ds_read_b128 v[168:171], v211 offset:33792
	ds_read_b128 v[182:185], v211 offset:34816
	ds_read_b128 v[186:189], v211 offset:35840
	ds_read_b128 v[190:193], v211 offset:36864
	ds_read_b128 v[194:197], v211 offset:37888
	ds_read_b128 v[198:201], v211 offset:38912
	ds_read_b128 v[202:205], v211 offset:39936
	buffer_load_dwordx4 v178, s[40:43], s67 offen lds
	s_mov_b32 m0, s23
	s_nop 0
	buffer_load_dwordx4 v206, s[40:43], s67 offen lds
	s_waitcnt vmcnt(8)
	s_waitcnt lgkmcnt(0)
	s_setprio 1
	s_barrier
	v_mfma_f32_16x16x32_bf16 v[158:161], v[106:109], v[164:167], v[158:161]
	v_mfma_f32_16x16x32_bf16 v[158:161], v[110:113], v[168:171], v[158:161]
	v_mfma_f32_16x16x32_bf16 v[154:157], v[114:117], v[164:167], v[154:157]
	v_mfma_f32_16x16x32_bf16 v[154:157], v[118:121], v[168:171], v[154:157]
	v_mfma_f32_16x16x32_bf16 v[146:149], v[114:117], v[182:185], v[146:149]
	v_mfma_f32_16x16x32_bf16 v[146:149], v[118:121], v[186:189], v[146:149]
	v_mfma_f32_16x16x32_bf16 v[150:153], v[106:109], v[182:185], v[150:153]
	v_mfma_f32_16x16x32_bf16 v[150:153], v[110:113], v[186:189], v[150:153]
	v_mfma_f32_16x16x32_bf16 v[138:141], v[106:109], v[190:193], v[138:141]
	v_mfma_f32_16x16x32_bf16 v[138:141], v[110:113], v[194:197], v[138:141]
	v_mfma_f32_16x16x32_bf16 v[134:137], v[114:117], v[190:193], v[134:137]
	v_mfma_f32_16x16x32_bf16 v[134:137], v[118:121], v[194:197], v[134:137]
	v_mfma_f32_16x16x32_bf16 v[98:101], v[114:117], v[198:201], v[98:101]
	v_mfma_f32_16x16x32_bf16 v[98:101], v[118:121], v[202:205], v[98:101]
	v_mfma_f32_16x16x32_bf16 v[102:105], v[106:109], v[198:201], v[102:105]
	v_mfma_f32_16x16x32_bf16 v[102:105], v[110:113], v[202:205], v[102:105]
	v_mfma_f32_16x16x32_bf16 v[62:65], v[122:125], v[164:167], v[62:65]
	v_mfma_f32_16x16x32_bf16 v[62:65], v[126:129], v[168:171], v[62:65]
	v_mfma_f32_16x16x32_bf16 v[58:61], v[130:133], v[164:167], v[58:61]
	v_mfma_f32_16x16x32_bf16 v[58:61], v[142:145], v[168:171], v[58:61]
	v_mfma_f32_16x16x32_bf16 v[50:53], v[130:133], v[182:185], v[50:53]
	v_mfma_f32_16x16x32_bf16 v[50:53], v[142:145], v[186:189], v[50:53]
	v_mfma_f32_16x16x32_bf16 v[54:57], v[122:125], v[182:185], v[54:57]
	v_mfma_f32_16x16x32_bf16 v[54:57], v[126:129], v[186:189], v[54:57]
	v_mfma_f32_16x16x32_bf16 v[46:49], v[122:125], v[190:193], v[46:49]
	v_mfma_f32_16x16x32_bf16 v[46:49], v[126:129], v[194:197], v[46:49]
	v_mfma_f32_16x16x32_bf16 v[42:45], v[130:133], v[190:193], v[42:45]
	v_mfma_f32_16x16x32_bf16 v[42:45], v[142:145], v[194:197], v[42:45]
	v_mfma_f32_16x16x32_bf16 v[34:37], v[130:133], v[198:201], v[34:37]
	v_mfma_f32_16x16x32_bf16 v[34:37], v[142:145], v[202:205], v[34:37]
	v_mfma_f32_16x16x32_bf16 v[38:41], v[122:125], v[198:201], v[38:41]
	v_mfma_f32_16x16x32_bf16 v[38:41], v[126:129], v[202:205], v[38:41]
	s_barrier
	s_setprio 0
	s_mov_b32 m0, s54
	s_or_b32 s67, s66, 0x80
	ds_read_b128 v[164:167], v211 offset:49152
	ds_read_b128 v[168:171], v211 offset:50176
	ds_read_b128 v[182:185], v211 offset:51200
	ds_read_b128 v[186:189], v211 offset:52224
	ds_read_b128 v[190:193], v211 offset:53248
	ds_read_b128 v[194:197], v211 offset:54272
	ds_read_b128 v[198:201], v211 offset:55296
	ds_read_b128 v[202:205], v211 offset:56320
	buffer_load_dwordx4 v179, s[44:47], s67 offen lds
	s_mov_b32 m0, s55
	s_add_i32 s66, s66, 0x80080
	buffer_load_dwordx4 v207, s[44:47], s67 offen lds
	s_mov_b32 m0, s74
	s_nop 0
	buffer_load_dwordx4 v179, s[44:47], s66 offen lds
	s_mov_b32 m0, s75
	s_nop 0
	buffer_load_dwordx4 v207, s[44:47], s66 offen lds
	s_mov_b32 m0, s72
	s_cmp_eq_u32 s64, 28
	buffer_load_dwordx4 v178, s[40:43], s65 offen lds
	s_mov_b32 m0, s73
	s_cselect_b64 vcc, s[50:51], 0
	buffer_load_dwordx4 v206, s[40:43], s65 offen lds
	s_waitcnt vmcnt(8)
	s_waitcnt lgkmcnt(0)
	s_setprio 1
	s_barrier
	v_mfma_f32_16x16x32_bf16 v[94:97], v[106:109], v[164:167], v[94:97]
	v_mfma_f32_16x16x32_bf16 v[94:97], v[110:113], v[168:171], v[94:97]
	v_mfma_f32_16x16x32_bf16 v[90:93], v[114:117], v[164:167], v[90:93]
	v_mfma_f32_16x16x32_bf16 v[90:93], v[118:121], v[168:171], v[90:93]
	v_mfma_f32_16x16x32_bf16 v[82:85], v[114:117], v[182:185], v[82:85]
	v_mfma_f32_16x16x32_bf16 v[82:85], v[118:121], v[186:189], v[82:85]
	v_mfma_f32_16x16x32_bf16 v[86:89], v[106:109], v[182:185], v[86:89]
	v_mfma_f32_16x16x32_bf16 v[86:89], v[110:113], v[186:189], v[86:89]
	v_mfma_f32_16x16x32_bf16 v[78:81], v[106:109], v[190:193], v[78:81]
	v_mfma_f32_16x16x32_bf16 v[78:81], v[110:113], v[194:197], v[78:81]
	v_mfma_f32_16x16x32_bf16 v[74:77], v[114:117], v[190:193], v[74:77]
	v_mfma_f32_16x16x32_bf16 v[74:77], v[118:121], v[194:197], v[74:77]
	v_mfma_f32_16x16x32_bf16 v[66:69], v[114:117], v[198:201], v[66:69]
	v_mfma_f32_16x16x32_bf16 v[66:69], v[118:121], v[202:205], v[66:69]
	v_mfma_f32_16x16x32_bf16 v[70:73], v[106:109], v[198:201], v[70:73]
	v_mfma_f32_16x16x32_bf16 v[70:73], v[110:113], v[202:205], v[70:73]
	v_mfma_f32_16x16x32_bf16 v[30:33], v[122:125], v[164:167], v[30:33]
	v_mfma_f32_16x16x32_bf16 v[30:33], v[126:129], v[168:171], v[30:33]
	v_mfma_f32_16x16x32_bf16 v[26:29], v[130:133], v[164:167], v[26:29]
	v_mfma_f32_16x16x32_bf16 v[26:29], v[142:145], v[168:171], v[26:29]
	v_mfma_f32_16x16x32_bf16 v[18:21], v[130:133], v[182:185], v[18:21]
	v_mfma_f32_16x16x32_bf16 v[18:21], v[142:145], v[186:189], v[18:21]
	v_mfma_f32_16x16x32_bf16 v[22:25], v[122:125], v[182:185], v[22:25]
	v_mfma_f32_16x16x32_bf16 v[22:25], v[126:129], v[186:189], v[22:25]
	v_mfma_f32_16x16x32_bf16 v[14:17], v[122:125], v[190:193], v[14:17]
	v_mfma_f32_16x16x32_bf16 v[14:17], v[126:129], v[194:197], v[14:17]
	v_mfma_f32_16x16x32_bf16 v[10:13], v[130:133], v[190:193], v[10:13]
	v_mfma_f32_16x16x32_bf16 v[10:13], v[142:145], v[194:197], v[10:13]
	v_mfma_f32_16x16x32_bf16 v[2:5], v[130:133], v[198:201], v[2:5]
	v_mfma_f32_16x16x32_bf16 v[2:5], v[142:145], v[202:205], v[2:5]
	v_mfma_f32_16x16x32_bf16 v[6:9], v[122:125], v[198:201], v[6:9]
	v_mfma_f32_16x16x32_bf16 v[6:9], v[126:129], v[202:205], v[6:9]
	s_cbranch_vccnz .Lee_skip_1529
	s_barrier
.Lee_skip_1529:
	s_setprio 0
	s_add_i32 s64, s64, 2
	s_addk_i32 s59, 0x100
	s_addk_i32 s63, 0x100
	s_cmp_gt_u32 s64, 29
	s_cbranch_scc0 .LBB0_1529

; #define PG8_STAGEX(rs, bufoff, soff, voff) do { _Pragma("unroll") for (int _i = 0; _i < 2; ++_i) \
;         __builtin_amdgcn_raw_ptr_buffer_load_lds(rs, (LAS unsigned*)(lds + (bufoff) + ldsw + _i * 8192), 16, (voff)[_i], (soff), 0, 0); } while (0)
; #define PG8_LDA(dst, b, h) do { _Pragma("unroll") for (int m = 0; m < 4; ++m) _Pragma("unroll") for (int k = 0; k < 2; ++k) dst[m][k] = *(const LAS bf16x8*)(lds + PG8_SA(b, h) + aoff + m * 2048 + k * 1024); } while (0)
; #define PG8_LDB(dst, b, h) do { _Pragma("unroll") for (int n = 0; n < 2; ++n) _Pragma("unroll") for (int k = 0; k < 2; ++k) dst[n][k] = *(const LAS bf16x8*)(lds + PG8_SB(b, h) + boff + n * 2048 + k * 1024); } while (0)
; #define PG8_WAIT_V(n) asm volatile("s_waitcnt vmcnt(" #n ")" ::: "memory")
; #define PG8_WAIT_L(n) asm volatile("s_waitcnt lgkmcnt(" #n ")" ::: "memory")
; #define PG8_BAR __builtin_amdgcn_s_barrier()
; #define PG8_SCHED __builtin_amdgcn_sched_barrier(0)
;     ...
;             const unsigned a1 = cA + (unsigned)(t + 1) * kstep;
;             const unsigned a2 = last ? nA : cA + (unsigned)(t + 2) * kstep, b2 = last ? nB : cB + (unsigned)(t + 2) * kstep;
;             const unsigned a3 = a2 + kstep, b3 = b2 + kstep;
;             PG8_LDB(B0, 0, 0); PG8_LDB(B1, 0, 1); PG8_SCHED; PG8_LDA(At, 0, 0); PG8_STAGEX(rsA, PG8_SA(1, 1), a1 + hstepA, voffA);
;             PG8_WAIT_V(8); PG8_WAIT_L(0); PG8_BAR; PG8_MMA(0, 0, At, B0); PG8_MMA(0, 1, At, B1); PG8_BAR; PG8_SCHED;
;             PG8_LDA(At, 0, 1); PG8_STAGEX(rsB, PG8_SB(0, 0), b2, voffB); PG8_STAGEX(rsB, PG8_SB(0, 1), b2 + hstepB, voffB); PG8_STAGEX(rsA, PG8_SA(0, 0), a2, voffA);
;             PG8_WAIT_V(8); PG8_WAIT_L(0); PG8_BAR; PG8_MMA(1, 0, At, B0); PG8_MMA(1, 1, At, B1); PG8_BAR; PG8_SCHED;
.LBB0_1651:
	v_add_u32_e32 v102, 0x10000, v172
	v_add_u32_e32 v146, 0x14000, v172
	ds_read_b128 v[82:85], v102
	ds_read_b128 v[86:89], v102 offset:1024
	ds_read_b128 v[98:101], v102 offset:2048
	ds_read_b128 v[102:105], v102 offset:3072
	ds_read_b128 v[150:153], v146
	ds_read_b128 v[154:157], v146 offset:1024
	ds_read_b128 v[182:185], v146 offset:2048
	ds_read_b128 v[186:189], v146 offset:3072
	s_add_i32 s42, s61, 0xfff80080
	s_cmp_eq_u32 s63, 28
	s_cselect_b32 s66, s30, s42
	s_cselect_b32 s65, s31, s62
	s_or_b32 s64, s66, 0x80
	s_mov_b32 m0, s29
	ds_read_b128 v[190:193], v173
	ds_read_b128 v[194:197], v173 offset:1024
	ds_read_b128 v[198:201], v173 offset:2048
	ds_read_b128 v[202:205], v173 offset:3072
	ds_read_b128 v[206:209], v173 offset:4096
	ds_read_b128 v[210:213], v173 offset:5120
	ds_read_b128 v[214:217], v173 offset:6144
	ds_read_b128 v[218:221], v173 offset:7168
	buffer_load_dwordx4 v159, s[76:79], s61 offen lds
	s_mov_b32 m0, s50
	s_nop 0
	buffer_load_dwordx4 v163, s[76:79], s61 offen lds
	s_waitcnt vmcnt(8)
	s_waitcnt lgkmcnt(0)
	s_setprio 1
	s_barrier
	v_mfma_f32_16x16x32_bf16 v[142:145], v[82:85], v[190:193], v[142:145]
	v_mfma_f32_16x16x32_bf16 v[142:145], v[86:89], v[194:197], v[142:145]
	v_mfma_f32_16x16x32_bf16 v[134:137], v[98:101], v[190:193], v[134:137]
	v_mfma_f32_16x16x32_bf16 v[134:137], v[102:105], v[194:197], v[134:137]
	v_mfma_f32_16x16x32_bf16 v[118:121], v[98:101], v[198:201], v[118:121]
	v_mfma_f32_16x16x32_bf16 v[118:121], v[102:105], v[202:205], v[118:121]
	v_mfma_f32_16x16x32_bf16 v[126:129], v[82:85], v[198:201], v[126:129]
	v_mfma_f32_16x16x32_bf16 v[126:129], v[86:89], v[202:205], v[126:129]
	v_mfma_f32_16x16x32_bf16 v[110:113], v[82:85], v[206:209], v[110:113]
	v_mfma_f32_16x16x32_bf16 v[110:113], v[86:89], v[210:213], v[110:113]
	v_mfma_f32_16x16x32_bf16 v[94:97], v[98:101], v[206:209], v[94:97]
	v_mfma_f32_16x16x32_bf16 v[94:97], v[102:105], v[210:213], v[94:97]
	v_mfma_f32_16x16x32_bf16 v[70:73], v[98:101], v[214:217], v[70:73]
	v_mfma_f32_16x16x32_bf16 v[70:73], v[102:105], v[218:221], v[70:73]
	v_mfma_f32_16x16x32_bf16 v[78:81], v[82:85], v[214:217], v[78:81]
	v_mfma_f32_16x16x32_bf16 v[78:81], v[86:89], v[218:221], v[78:81]
	v_mfma_f32_16x16x32_bf16 v[138:141], v[150:153], v[190:193], v[138:141]
	v_mfma_f32_16x16x32_bf16 v[138:141], v[154:157], v[194:197], v[138:141]
	v_mfma_f32_16x16x32_bf16 v[130:133], v[182:185], v[190:193], v[130:133]
	v_mfma_f32_16x16x32_bf16 v[130:133], v[186:189], v[194:197], v[130:133]
	v_mfma_f32_16x16x32_bf16 v[114:117], v[182:185], v[198:201], v[114:117]
	v_mfma_f32_16x16x32_bf16 v[114:117], v[186:189], v[202:205], v[114:117]
	v_mfma_f32_16x16x32_bf16 v[122:125], v[150:153], v[198:201], v[122:125]
	v_mfma_f32_16x16x32_bf16 v[122:125], v[154:157], v[202:205], v[122:125]
	v_mfma_f32_16x16x32_bf16 v[106:109], v[150:153], v[206:209], v[106:109]
	v_mfma_f32_16x16x32_bf16 v[106:109], v[154:157], v[210:213], v[106:109]
	v_mfma_f32_16x16x32_bf16 v[90:93], v[182:185], v[206:209], v[90:93]
	v_mfma_f32_16x16x32_bf16 v[90:93], v[186:189], v[210:213], v[90:93]
	v_mfma_f32_16x16x32_bf16 v[66:69], v[182:185], v[214:217], v[66:69]
	v_mfma_f32_16x16x32_bf16 v[66:69], v[186:189], v[218:221], v[66:69]
	v_mfma_f32_16x16x32_bf16 v[74:77], v[150:153], v[214:217], v[74:77]
	v_mfma_f32_16x16x32_bf16 v[74:77], v[154:157], v[218:221], v[74:77]
	s_barrier
	s_setprio 0
	s_mov_b32 m0, s16
	s_mov_b32 s42, s78
	s_mov_b32 s43, s79
	ds_read_b128 v[190:193], v173 offset:16384
	ds_read_b128 v[194:197], v173 offset:17408
	ds_read_b128 v[198:201], v173 offset:18432
	ds_read_b128 v[202:205], v173 offset:19456
	ds_read_b128 v[206:209], v173 offset:20480
	ds_read_b128 v[210:213], v173 offset:21504
	ds_read_b128 v[214:217], v173 offset:22528
	ds_read_b128 v[218:221], v173 offset:23552
	buffer_load_dwordx4 v161, s[40:43], s65 offen lds
	s_mov_b32 m0, s17
	s_add_i32 s67, s65, 0x80000
	buffer_load_dwordx4 v165, s[40:43], s65 offen lds
	s_mov_b32 m0, s18
	s_nop 0
	buffer_load_dwordx4 v161, s[40:43], s67 offen lds
	s_mov_b32 m0, s19
	s_nop 0
	buffer_load_dwordx4 v165, s[40:43], s67 offen lds
	s_mov_b32 m0, s15
	s_nop 0
	buffer_load_dwordx4 v159, s[76:79], s66 offen lds
	s_mov_b32 m0, s20
	s_nop 0
	buffer_load_dwordx4 v163, s[76:79], s66 offen lds
	s_waitcnt vmcnt(8)
	s_waitcnt lgkmcnt(0)
	s_setprio 1
	s_barrier
	v_mfma_f32_16x16x32_bf16 v[62:65], v[82:85], v[190:193], v[62:65]
	v_mfma_f32_16x16x32_bf16 v[62:65], v[86:89], v[194:197], v[62:65]
	v_mfma_f32_16x16x32_bf16 v[54:57], v[98:101], v[190:193], v[54:57]
	v_mfma_f32_16x16x32_bf16 v[54:57], v[102:105], v[194:197], v[54:57]
	v_mfma_f32_16x16x32_bf16 v[38:41], v[98:101], v[198:201], v[38:41]
	v_mfma_f32_16x16x32_bf16 v[38:41], v[102:105], v[202:205], v[38:41]
	v_mfma_f32_16x16x32_bf16 v[46:49], v[82:85], v[198:201], v[46:49]
	v_mfma_f32_16x16x32_bf16 v[46:49], v[86:89], v[202:205], v[46:49]
	v_mfma_f32_16x16x32_bf16 v[30:33], v[82:85], v[206:209], v[30:33]
	v_mfma_f32_16x16x32_bf16 v[30:33], v[86:89], v[210:213], v[30:33]
	v_mfma_f32_16x16x32_bf16 v[22:25], v[98:101], v[206:209], v[22:25]
	v_mfma_f32_16x16x32_bf16 v[22:25], v[102:105], v[210:213], v[22:25]
	v_mfma_f32_16x16x32_bf16 v[6:9], v[98:101], v[214:217], v[6:9]
	v_mfma_f32_16x16x32_bf16 v[6:9], v[102:105], v[218:221], v[6:9]
	v_mfma_f32_16x16x32_bf16 v[14:17], v[82:85], v[214:217], v[14:17]
	v_mfma_f32_16x16x32_bf16 v[14:17], v[86:89], v[218:221], v[14:17]
	v_mfma_f32_16x16x32_bf16 v[58:61], v[150:153], v[190:193], v[58:61]
	v_mfma_f32_16x16x32_bf16 v[58:61], v[154:157], v[194:197], v[58:61]
	v_mfma_f32_16x16x32_bf16 v[50:53], v[182:185], v[190:193], v[50:53]
	v_mfma_f32_16x16x32_bf16 v[50:53], v[186:189], v[194:197], v[50:53]
	v_mfma_f32_16x16x32_bf16 v[34:37], v[182:185], v[198:201], v[34:37]
	v_mfma_f32_16x16x32_bf16 v[34:37], v[186:189], v[202:205], v[34:37]
	v_mfma_f32_16x16x32_bf16 v[42:45], v[150:153], v[198:201], v[42:45]
	v_mfma_f32_16x16x32_bf16 v[42:45], v[154:157], v[202:205], v[42:45]
	v_mfma_f32_16x16x32_bf16 v[26:29], v[150:153], v[206:209], v[26:29]
	v_mfma_f32_16x16x32_bf16 v[26:29], v[154:157], v[210:213], v[26:29]
	v_mfma_f32_16x16x32_bf16 v[18:21], v[182:185], v[206:209], v[18:21]
	v_mfma_f32_16x16x32_bf16 v[18:21], v[186:189], v[210:213], v[18:21]
	v_mfma_f32_16x16x32_bf16 v[2:5], v[182:185], v[214:217], v[2:5]
	v_mfma_f32_16x16x32_bf16 v[2:5], v[186:189], v[218:221], v[2:5]
	v_mfma_f32_16x16x32_bf16 v[10:13], v[150:153], v[214:217], v[10:13]
	v_mfma_f32_16x16x32_bf16 v[10:13], v[154:157], v[218:221], v[10:13]
	s_barrier
; #define PG8_STAGEX(rs, bufoff, soff, voff) do { _Pragma("unroll") for (int _i = 0; _i < 2; ++_i) \
;         __builtin_amdgcn_raw_ptr_buffer_load_lds(rs, (LAS unsigned*)(lds + (bufoff) + ldsw + _i * 8192), 16, (voff)[_i], (soff), 0, 0); } while (0)
; #define PG8_LDA(dst, b, h) do { _Pragma("unroll") for (int m = 0; m < 4; ++m) _Pragma("unroll") for (int k = 0; k < 2; ++k) dst[m][k] = *(const LAS bf16x8*)(lds + PG8_SA(b, h) + aoff + m * 2048 + k * 1024); } while (0)
; #define PG8_LDB(dst, b, h) do { _Pragma("unroll") for (int n = 0; n < 2; ++n) _Pragma("unroll") for (int k = 0; k < 2; ++k) dst[n][k] = *(const LAS bf16x8*)(lds + PG8_SB(b, h) + boff + n * 2048 + k * 1024); } while (0)
; #define PG8_WAIT_V(n) asm volatile("s_waitcnt vmcnt(" #n ")" ::: "memory")
; #define PG8_WAIT_L(n) asm volatile("s_waitcnt lgkmcnt(" #n ")" ::: "memory")
; #define PG8_BAR __builtin_amdgcn_s_barrier()
; #define PG8_SCHED __builtin_amdgcn_sched_barrier(0)
;     ...
;             PG8_LDB(B0, 1, 0); PG8_LDB(B1, 1, 1); PG8_SCHED; PG8_LDA(At, 1, 0); PG8_STAGEX(rsA, PG8_SA(0, 1), a2 + hstepA, voffA);
;             PG8_WAIT_V(8); PG8_WAIT_L(0); PG8_BAR; PG8_MMA(0, 0, At, B0); PG8_MMA(0, 1, At, B1); PG8_BAR; PG8_SCHED;
;             PG8_LDA(At, 1, 1); PG8_STAGEX(rsB, PG8_SB(1, 0), b3, voffB); PG8_STAGEX(rsB, PG8_SB(1, 1), b3 + hstepB, voffB); PG8_STAGEX(rsA, PG8_SA(1, 0), a3, voffA);
;             PG8_WAIT_V(8); PG8_WAIT_L(0); PG8_BAR; PG8_MMA(1, 0, At, B0); PG8_MMA(1, 1, At, B1); PG8_BAR; PG8_SCHED;
;         }
;     ...
;         if (wr == 0) PG8_BAR;
	s_setprio 0
	v_add_u32_e32 v102, 0x18000, v172
	v_add_u32_e32 v146, 0x1c000, v172
	ds_read_b128 v[82:85], v102
	ds_read_b128 v[86:89], v102 offset:1024
	ds_read_b128 v[98:101], v102 offset:2048
	ds_read_b128 v[102:105], v102 offset:3072
	ds_read_b128 v[150:153], v146
	ds_read_b128 v[154:157], v146 offset:1024
	ds_read_b128 v[182:185], v146 offset:2048
	ds_read_b128 v[186:189], v146 offset:3072
	s_add_i32 s66, s66, 0x80000
	s_mov_b32 m0, s21
	ds_read_b128 v[190:193], v173 offset:32768
	ds_read_b128 v[194:197], v173 offset:33792
	ds_read_b128 v[198:201], v173 offset:34816
	ds_read_b128 v[202:205], v173 offset:35840
	ds_read_b128 v[206:209], v173 offset:36864
	ds_read_b128 v[210:213], v173 offset:37888
	ds_read_b128 v[214:217], v173 offset:38912
	ds_read_b128 v[218:221], v173 offset:39936
	buffer_load_dwordx4 v159, s[76:79], s66 offen lds
	s_mov_b32 m0, s22
	s_nop 0
	buffer_load_dwordx4 v163, s[76:79], s66 offen lds
	s_waitcnt vmcnt(8)
	s_waitcnt lgkmcnt(0)
	s_setprio 1
	s_barrier
	v_mfma_f32_16x16x32_bf16 v[142:145], v[82:85], v[190:193], v[142:145]
	v_mfma_f32_16x16x32_bf16 v[142:145], v[86:89], v[194:197], v[142:145]
	v_mfma_f32_16x16x32_bf16 v[134:137], v[98:101], v[190:193], v[134:137]
	v_mfma_f32_16x16x32_bf16 v[134:137], v[102:105], v[194:197], v[134:137]
	v_mfma_f32_16x16x32_bf16 v[118:121], v[98:101], v[198:201], v[118:121]
	v_mfma_f32_16x16x32_bf16 v[118:121], v[102:105], v[202:205], v[118:121]
	v_mfma_f32_16x16x32_bf16 v[126:129], v[82:85], v[198:201], v[126:129]
	v_mfma_f32_16x16x32_bf16 v[126:129], v[86:89], v[202:205], v[126:129]
	v_mfma_f32_16x16x32_bf16 v[110:113], v[82:85], v[206:209], v[110:113]
	v_mfma_f32_16x16x32_bf16 v[110:113], v[86:89], v[210:213], v[110:113]
	v_mfma_f32_16x16x32_bf16 v[94:97], v[98:101], v[206:209], v[94:97]
	v_mfma_f32_16x16x32_bf16 v[94:97], v[102:105], v[210:213], v[94:97]
	v_mfma_f32_16x16x32_bf16 v[70:73], v[98:101], v[214:217], v[70:73]
	v_mfma_f32_16x16x32_bf16 v[70:73], v[102:105], v[218:221], v[70:73]
	v_mfma_f32_16x16x32_bf16 v[78:81], v[82:85], v[214:217], v[78:81]
	v_mfma_f32_16x16x32_bf16 v[78:81], v[86:89], v[218:221], v[78:81]
	v_mfma_f32_16x16x32_bf16 v[138:141], v[150:153], v[190:193], v[138:141]
	v_mfma_f32_16x16x32_bf16 v[138:141], v[154:157], v[194:197], v[138:141]
	v_mfma_f32_16x16x32_bf16 v[130:133], v[182:185], v[190:193], v[130:133]
	v_mfma_f32_16x16x32_bf16 v[130:133], v[186:189], v[194:197], v[130:133]
	v_mfma_f32_16x16x32_bf16 v[114:117], v[182:185], v[198:201], v[114:117]
	v_mfma_f32_16x16x32_bf16 v[114:117], v[186:189], v[202:205], v[114:117]
	v_mfma_f32_16x16x32_bf16 v[122:125], v[150:153], v[198:201], v[122:125]
	v_mfma_f32_16x16x32_bf16 v[122:125], v[154:157], v[202:205], v[122:125]
	v_mfma_f32_16x16x32_bf16 v[106:109], v[150:153], v[206:209], v[106:109]
	v_mfma_f32_16x16x32_bf16 v[106:109], v[154:157], v[210:213], v[106:109]
	v_mfma_f32_16x16x32_bf16 v[90:93], v[182:185], v[206:209], v[90:93]
	v_mfma_f32_16x16x32_bf16 v[90:93], v[186:189], v[210:213], v[90:93]
	v_mfma_f32_16x16x32_bf16 v[66:69], v[182:185], v[214:217], v[66:69]
	v_mfma_f32_16x16x32_bf16 v[66:69], v[186:189], v[218:221], v[66:69]
	v_mfma_f32_16x16x32_bf16 v[74:77], v[150:153], v[214:217], v[74:77]
	v_mfma_f32_16x16x32_bf16 v[74:77], v[154:157], v[218:221], v[74:77]
	s_barrier
	s_setprio 0
	s_mov_b32 m0, s23
	s_or_b32 s66, s65, 0x80
	ds_read_b128 v[190:193], v173 offset:49152
	ds_read_b128 v[194:197], v173 offset:50176
	ds_read_b128 v[198:201], v173 offset:51200
	ds_read_b128 v[202:205], v173 offset:52224
	ds_read_b128 v[206:209], v173 offset:53248
	ds_read_b128 v[210:213], v173 offset:54272
	ds_read_b128 v[214:217], v173 offset:55296
	ds_read_b128 v[218:221], v173 offset:56320
	buffer_load_dwordx4 v161, s[40:43], s66 offen lds
	s_mov_b32 m0, s24
	s_add_i32 s65, s65, 0x80080
	buffer_load_dwordx4 v165, s[40:43], s66 offen lds
	s_mov_b32 m0, s27
	s_nop 0
	buffer_load_dwordx4 v161, s[40:43], s65 offen lds
	s_mov_b32 m0, s28
	s_nop 0
	buffer_load_dwordx4 v165, s[40:43], s65 offen lds
	s_mov_b32 m0, s25
	s_cmp_eq_u32 s63, 28
	buffer_load_dwordx4 v159, s[76:79], s64 offen lds
	s_mov_b32 m0, s26
	s_cselect_b64 vcc, s[46:47], 0
	buffer_load_dwordx4 v163, s[76:79], s64 offen lds
	s_waitcnt vmcnt(8)
	s_waitcnt lgkmcnt(0)
	s_setprio 1
	s_barrier
	v_mfma_f32_16x16x32_bf16 v[62:65], v[82:85], v[190:193], v[62:65]
	v_mfma_f32_16x16x32_bf16 v[62:65], v[86:89], v[194:197], v[62:65]
	v_mfma_f32_16x16x32_bf16 v[54:57], v[98:101], v[190:193], v[54:57]
	v_mfma_f32_16x16x32_bf16 v[54:57], v[102:105], v[194:197], v[54:57]
	v_mfma_f32_16x16x32_bf16 v[38:41], v[98:101], v[198:201], v[38:41]
	v_mfma_f32_16x16x32_bf16 v[38:41], v[102:105], v[202:205], v[38:41]
	v_mfma_f32_16x16x32_bf16 v[46:49], v[82:85], v[198:201], v[46:49]
	v_mfma_f32_16x16x32_bf16 v[46:49], v[86:89], v[202:205], v[46:49]
	v_mfma_f32_16x16x32_bf16 v[30:33], v[82:85], v[206:209], v[30:33]
	v_mfma_f32_16x16x32_bf16 v[30:33], v[86:89], v[210:213], v[30:33]
	v_mfma_f32_16x16x32_bf16 v[22:25], v[98:101], v[206:209], v[22:25]
	v_mfma_f32_16x16x32_bf16 v[22:25], v[102:105], v[210:213], v[22:25]
	v_mfma_f32_16x16x32_bf16 v[6:9], v[98:101], v[214:217], v[6:9]
	v_mfma_f32_16x16x32_bf16 v[6:9], v[102:105], v[218:221], v[6:9]
	v_mfma_f32_16x16x32_bf16 v[14:17], v[82:85], v[214:217], v[14:17]
	v_mfma_f32_16x16x32_bf16 v[14:17], v[86:89], v[218:221], v[14:17]
	v_mfma_f32_16x16x32_bf16 v[58:61], v[150:153], v[190:193], v[58:61]
	v_mfma_f32_16x16x32_bf16 v[58:61], v[154:157], v[194:197], v[58:61]
	v_mfma_f32_16x16x32_bf16 v[50:53], v[182:185], v[190:193], v[50:53]
	v_mfma_f32_16x16x32_bf16 v[50:53], v[186:189], v[194:197], v[50:53]
	v_mfma_f32_16x16x32_bf16 v[34:37], v[182:185], v[198:201], v[34:37]
	v_mfma_f32_16x16x32_bf16 v[34:37], v[186:189], v[202:205], v[34:37]
	v_mfma_f32_16x16x32_bf16 v[42:45], v[150:153], v[198:201], v[42:45]
	v_mfma_f32_16x16x32_bf16 v[42:45], v[154:157], v[202:205], v[42:45]
	v_mfma_f32_16x16x32_bf16 v[26:29], v[150:153], v[206:209], v[26:29]
	v_mfma_f32_16x16x32_bf16 v[26:29], v[154:157], v[210:213], v[26:29]
	v_mfma_f32_16x16x32_bf16 v[18:21], v[182:185], v[206:209], v[18:21]
	v_mfma_f32_16x16x32_bf16 v[18:21], v[186:189], v[210:213], v[18:21]
	v_mfma_f32_16x16x32_bf16 v[2:5], v[182:185], v[214:217], v[2:5]
	v_mfma_f32_16x16x32_bf16 v[2:5], v[186:189], v[218:221], v[2:5]
	v_mfma_f32_16x16x32_bf16 v[10:13], v[150:153], v[214:217], v[10:13]
	v_mfma_f32_16x16x32_bf16 v[10:13], v[154:157], v[218:221], v[10:13]
	s_cbranch_vccnz .Lee_skip_1651
	s_barrier
.Lee_skip_1651:
	s_setprio 0
	s_add_i32 s63, s63, 2
	s_addk_i32 s61, 0x100
	s_addk_i32 s62, 0x100
	s_cmp_gt_u32 s63, 29
	s_cbranch_scc0 .LBB0_1651

; #define PG8_STAGEX(rs, bufoff, soff, voff) do { _Pragma("unroll") for (int _i = 0; _i < 2; ++_i) \
;         __builtin_amdgcn_raw_ptr_buffer_load_lds(rs, (LAS unsigned*)(lds + (bufoff) + ldsw + _i * 8192), 16, (voff)[_i], (soff), 0, 0); } while (0)
; #define PG8_LDA(dst, b, h) do { _Pragma("unroll") for (int m = 0; m < 4; ++m) _Pragma("unroll") for (int k = 0; k < 2; ++k) dst[m][k] = *(const LAS bf16x8*)(lds + PG8_SA(b, h) + aoff + m * 2048 + k * 1024); } while (0)
; #define PG8_LDB(dst, b, h) do { _Pragma("unroll") for (int n = 0; n < 2; ++n) _Pragma("unroll") for (int k = 0; k < 2; ++k) dst[n][k] = *(const LAS bf16x8*)(lds + PG8_SB(b, h) + boff + n * 2048 + k * 1024); } while (0)
; #define PG8_WAIT_V(n) asm volatile("s_waitcnt vmcnt(" #n ")" ::: "memory")
; #define PG8_WAIT_L(n) asm volatile("s_waitcnt lgkmcnt(" #n ")" ::: "memory")
; #define PG8_BAR __builtin_amdgcn_s_barrier()
; #define PG8_SCHED __builtin_amdgcn_sched_barrier(0)
;     ...
;             const unsigned a1 = cA + (unsigned)(t + 1) * kstep;
;             const unsigned a2 = last ? nA : cA + (unsigned)(t + 2) * kstep, b2 = last ? nB : cB + (unsigned)(t + 2) * kstep;
;             const unsigned a3 = a2 + kstep, b3 = b2 + kstep;
;             PG8_LDB(B0, 0, 0); PG8_LDB(B1, 0, 1); PG8_SCHED; PG8_LDA(At, 0, 0); PG8_STAGEX(rsA, PG8_SA(1, 1), a1 + hstepA, voffA);
;             PG8_WAIT_V(8); PG8_WAIT_L(0); PG8_BAR; PG8_MMA(0, 0, At, B0); PG8_MMA(0, 1, At, B1); PG8_BAR; PG8_SCHED;
;             PG8_LDA(At, 0, 1); PG8_STAGEX(rsB, PG8_SB(0, 0), b2, voffB); PG8_STAGEX(rsB, PG8_SB(0, 1), b2 + hstepB, voffB); PG8_STAGEX(rsA, PG8_SA(0, 0), a2, voffA);
;             PG8_WAIT_V(8); PG8_WAIT_L(0); PG8_BAR; PG8_MMA(1, 0, At, B0); PG8_MMA(1, 1, At, B1); PG8_BAR; PG8_SCHED;
.LBB0_1750:
	v_add_u32_e32 v70, 0x10000, v241
	ds_read_b128 v[134:137], v70
	ds_read_b128 v[138:141], v70 offset:1024
	ds_read_b128 v[142:145], v70 offset:2048
	ds_read_b128 v[146:149], v70 offset:3072
	v_add_u32_e32 v70, 0x14000, v241
	ds_read_b128 v[150:153], v70
	ds_read_b128 v[154:157], v70 offset:1024
	ds_read_b128 v[158:161], v70 offset:2048
	ds_read_b128 v[162:165], v70 offset:3072
	s_add_i32 s46, s40, 0xffea8080
	s_cmpk_eq_i32 s60, 0x52
	s_cselect_b32 s63, s30, s46
	s_cselect_b32 s62, s31, s41
	s_or_b32 s61, s63, 0x80
	s_mov_b32 m0, s72
	ds_read_b128 v[166:169], v242
	ds_read_b128 v[170:173], v242 offset:1024
	ds_read_b128 v[184:187], v242 offset:2048
	ds_read_b128 v[188:191], v242 offset:3072
	ds_read_b128 v[192:195], v242 offset:4096
	ds_read_b128 v[196:199], v242 offset:5120
	ds_read_b128 v[200:203], v242 offset:6144
	ds_read_b128 v[204:207], v242 offset:7168
	buffer_load_dwordx4 v178, s[76:79], s40 offen lds
	s_mov_b32 m0, s73
	s_nop 0
	buffer_load_dwordx4 v237, s[76:79], s40 offen lds
	s_waitcnt vmcnt(8)
	s_waitcnt lgkmcnt(0)
	s_setprio 1
	s_barrier
	v_mfma_f32_16x16x32_bf16 v[130:133], v[134:137], v[166:169], v[130:133]
	v_mfma_f32_16x16x32_bf16 v[130:133], v[138:141], v[170:173], v[130:133]
	v_mfma_f32_16x16x32_bf16 v[126:129], v[142:145], v[166:169], v[126:129]
	v_mfma_f32_16x16x32_bf16 v[126:129], v[146:149], v[170:173], v[126:129]
	v_mfma_f32_16x16x32_bf16 v[118:121], v[142:145], v[184:187], v[118:121]
	v_mfma_f32_16x16x32_bf16 v[118:121], v[146:149], v[188:191], v[118:121]
	v_mfma_f32_16x16x32_bf16 v[122:125], v[134:137], v[184:187], v[122:125]
	v_mfma_f32_16x16x32_bf16 v[122:125], v[138:141], v[188:191], v[122:125]
	v_mfma_f32_16x16x32_bf16 v[114:117], v[134:137], v[192:195], v[114:117]
	v_mfma_f32_16x16x32_bf16 v[114:117], v[138:141], v[196:199], v[114:117]
	v_mfma_f32_16x16x32_bf16 v[110:113], v[142:145], v[192:195], v[110:113]
	v_mfma_f32_16x16x32_bf16 v[110:113], v[146:149], v[196:199], v[110:113]
	v_mfma_f32_16x16x32_bf16 v[102:105], v[142:145], v[200:203], v[102:105]
	v_mfma_f32_16x16x32_bf16 v[102:105], v[146:149], v[204:207], v[102:105]
	v_mfma_f32_16x16x32_bf16 v[106:109], v[134:137], v[200:203], v[106:109]
	v_mfma_f32_16x16x32_bf16 v[106:109], v[138:141], v[204:207], v[106:109]
	v_mfma_f32_16x16x32_bf16 v[62:65], v[150:153], v[166:169], v[62:65]
	v_mfma_f32_16x16x32_bf16 v[62:65], v[154:157], v[170:173], v[62:65]
	v_mfma_f32_16x16x32_bf16 v[58:61], v[158:161], v[166:169], v[58:61]
	v_mfma_f32_16x16x32_bf16 v[58:61], v[162:165], v[170:173], v[58:61]
	v_mfma_f32_16x16x32_bf16 v[50:53], v[158:161], v[184:187], v[50:53]
	v_mfma_f32_16x16x32_bf16 v[50:53], v[162:165], v[188:191], v[50:53]
	v_mfma_f32_16x16x32_bf16 v[54:57], v[150:153], v[184:187], v[54:57]
	v_mfma_f32_16x16x32_bf16 v[54:57], v[154:157], v[188:191], v[54:57]
	v_mfma_f32_16x16x32_bf16 v[46:49], v[150:153], v[192:195], v[46:49]
	v_mfma_f32_16x16x32_bf16 v[46:49], v[154:157], v[196:199], v[46:49]
	v_mfma_f32_16x16x32_bf16 v[42:45], v[158:161], v[192:195], v[42:45]
	v_mfma_f32_16x16x32_bf16 v[42:45], v[162:165], v[196:199], v[42:45]
	v_mfma_f32_16x16x32_bf16 v[34:37], v[158:161], v[200:203], v[34:37]
	v_mfma_f32_16x16x32_bf16 v[34:37], v[162:165], v[204:207], v[34:37]
	v_mfma_f32_16x16x32_bf16 v[38:41], v[150:153], v[200:203], v[38:41]
	v_mfma_f32_16x16x32_bf16 v[38:41], v[154:157], v[204:207], v[38:41]
	s_barrier
	s_setprio 0
	s_mov_b32 m0, s17
	s_mov_b32 s46, s78
	s_mov_b32 s47, s79
	ds_read_b128 v[166:169], v242 offset:16384
	ds_read_b128 v[170:173], v242 offset:17408
	ds_read_b128 v[184:187], v242 offset:18432
	ds_read_b128 v[188:191], v242 offset:19456
	ds_read_b128 v[192:195], v242 offset:20480
	ds_read_b128 v[196:199], v242 offset:21504
	ds_read_b128 v[200:203], v242 offset:22528
	ds_read_b128 v[204:207], v242 offset:23552
	buffer_load_dwordx4 v179, s[44:47], s62 offen lds
	s_mov_b32 m0, s18
	s_add_i32 s64, s62, 0x158000
	buffer_load_dwordx4 v238, s[44:47], s62 offen lds
	s_mov_b32 m0, s19
	s_nop 0
	buffer_load_dwordx4 v179, s[44:47], s64 offen lds
	s_mov_b32 m0, s20
	s_nop 0
	buffer_load_dwordx4 v238, s[44:47], s64 offen lds
	s_mov_b32 m0, s16
	s_nop 0
	buffer_load_dwordx4 v178, s[76:79], s63 offen lds
	s_mov_b32 m0, s21
	s_nop 0
	buffer_load_dwordx4 v237, s[76:79], s63 offen lds
	s_waitcnt vmcnt(8)
	s_waitcnt lgkmcnt(0)
	s_setprio 1
	s_barrier
	v_mfma_f32_16x16x32_bf16 v[98:101], v[134:137], v[166:169], v[98:101]
	v_mfma_f32_16x16x32_bf16 v[94:97], v[142:145], v[166:169], v[94:97]
	v_mfma_f32_16x16x32_bf16 v[90:93], v[134:137], v[184:187], v[90:93]
	v_mfma_f32_16x16x32_bf16 v[86:89], v[142:145], v[184:187], v[86:89]
	v_mfma_f32_16x16x32_bf16 v[82:85], v[134:137], v[192:195], v[82:85]
	v_mfma_f32_16x16x32_bf16 v[76:79], v[142:145], v[192:195], v[78:81]
	v_mfma_f32_16x16x32_bf16 v[70:73], v[134:137], v[200:203], v[72:75]
	v_mfma_f32_16x16x32_bf16 v[66:69], v[142:145], v[200:203], v[66:69]
	v_mfma_f32_16x16x32_bf16 v[98:101], v[138:141], v[170:173], v[98:101]
	v_mfma_f32_16x16x32_bf16 v[94:97], v[146:149], v[170:173], v[94:97]
	v_mfma_f32_16x16x32_bf16 v[90:93], v[138:141], v[188:191], v[90:93]
	v_mfma_f32_16x16x32_bf16 v[86:89], v[146:149], v[188:191], v[86:89]
	v_mfma_f32_16x16x32_bf16 v[82:85], v[138:141], v[196:199], v[82:85]
	v_mfma_f32_16x16x32_bf16 v[76:79], v[146:149], v[196:199], v[76:79]
	v_mfma_f32_16x16x32_bf16 v[70:73], v[138:141], v[204:207], v[70:73]
	v_mfma_f32_16x16x32_bf16 v[66:69], v[146:149], v[204:207], v[66:69]
	v_mfma_f32_16x16x32_bf16 v[30:33], v[150:153], v[166:169], v[30:33]
	v_mfma_f32_16x16x32_bf16 v[26:29], v[158:161], v[166:169], v[26:29]
	v_mfma_f32_16x16x32_bf16 v[22:25], v[150:153], v[184:187], v[22:25]
	v_mfma_f32_16x16x32_bf16 v[18:21], v[158:161], v[184:187], v[18:21]
	v_mfma_f32_16x16x32_bf16 v[14:17], v[150:153], v[192:195], v[14:17]
	v_mfma_f32_16x16x32_bf16 v[10:13], v[158:161], v[192:195], v[10:13]
	v_mfma_f32_16x16x32_bf16 v[6:9], v[150:153], v[200:203], v[6:9]
	v_mfma_f32_16x16x32_bf16 v[2:5], v[158:161], v[200:203], v[2:5]
	v_mfma_f32_16x16x32_bf16 v[30:33], v[154:157], v[170:173], v[30:33]
	v_mfma_f32_16x16x32_bf16 v[26:29], v[162:165], v[170:173], v[26:29]
	v_mfma_f32_16x16x32_bf16 v[22:25], v[154:157], v[188:191], v[22:25]
	v_mfma_f32_16x16x32_bf16 v[18:21], v[162:165], v[188:191], v[18:21]
	v_mfma_f32_16x16x32_bf16 v[14:17], v[154:157], v[196:199], v[14:17]
	v_mfma_f32_16x16x32_bf16 v[10:13], v[162:165], v[196:199], v[10:13]
	v_mfma_f32_16x16x32_bf16 v[6:9], v[154:157], v[204:207], v[6:9]
	v_mfma_f32_16x16x32_bf16 v[2:5], v[162:165], v[204:207], v[2:5]
	s_barrier
; #define PG8_STAGEX(rs, bufoff, soff, voff) do { _Pragma("unroll") for (int _i = 0; _i < 2; ++_i) \
;         __builtin_amdgcn_raw_ptr_buffer_load_lds(rs, (LAS unsigned*)(lds + (bufoff) + ldsw + _i * 8192), 16, (voff)[_i], (soff), 0, 0); } while (0)
; #define PG8_LDA(dst, b, h) do { _Pragma("unroll") for (int m = 0; m < 4; ++m) _Pragma("unroll") for (int k = 0; k < 2; ++k) dst[m][k] = *(const LAS bf16x8*)(lds + PG8_SA(b, h) + aoff + m * 2048 + k * 1024); } while (0)
; #define PG8_LDB(dst, b, h) do { _Pragma("unroll") for (int n = 0; n < 2; ++n) _Pragma("unroll") for (int k = 0; k < 2; ++k) dst[n][k] = *(const LAS bf16x8*)(lds + PG8_SB(b, h) + boff + n * 2048 + k * 1024); } while (0)
; #define PG8_WAIT_V(n) asm volatile("s_waitcnt vmcnt(" #n ")" ::: "memory")
; #define PG8_WAIT_L(n) asm volatile("s_waitcnt lgkmcnt(" #n ")" ::: "memory")
; #define PG8_BAR __builtin_amdgcn_s_barrier()
; #define PG8_SCHED __builtin_amdgcn_sched_barrier(0)
;     ...
;             PG8_LDB(B0, 1, 0); PG8_LDB(B1, 1, 1); PG8_SCHED; PG8_LDA(At, 1, 0); PG8_STAGEX(rsA, PG8_SA(0, 1), a2 + hstepA, voffA);
;             PG8_WAIT_V(8); PG8_WAIT_L(0); PG8_BAR; PG8_MMA(0, 0, At, B0); PG8_MMA(0, 1, At, B1); PG8_BAR; PG8_SCHED;
;             PG8_LDA(At, 1, 1); PG8_STAGEX(rsB, PG8_SB(1, 0), b3, voffB); PG8_STAGEX(rsB, PG8_SB(1, 1), b3 + hstepB, voffB); PG8_STAGEX(rsA, PG8_SA(1, 0), a3, voffA);
;             PG8_WAIT_V(8); PG8_WAIT_L(0); PG8_BAR; PG8_MMA(1, 0, At, B0); PG8_MMA(1, 1, At, B1); PG8_BAR; PG8_SCHED;
;         }
;     ...
;         if (wr == 0) PG8_BAR;
	s_setprio 0
	v_add_u32_e32 v74, 0x18000, v241
	ds_read_b128 v[134:137], v74
	ds_read_b128 v[138:141], v74 offset:1024
	ds_read_b128 v[142:145], v74 offset:2048
	ds_read_b128 v[146:149], v74 offset:3072
	v_add_u32_e32 v74, 0x1c000, v241
	ds_read_b128 v[150:153], v74
	ds_read_b128 v[154:157], v74 offset:1024
	ds_read_b128 v[158:161], v74 offset:2048
	ds_read_b128 v[162:165], v74 offset:3072
	s_add_i32 s63, s63, 0x158000
	s_mov_b32 m0, s22
	ds_read_b128 v[166:169], v242 offset:32768
	ds_read_b128 v[170:173], v242 offset:33792
	ds_read_b128 v[184:187], v242 offset:34816
	ds_read_b128 v[188:191], v242 offset:35840
	ds_read_b128 v[192:195], v242 offset:36864
	ds_read_b128 v[196:199], v242 offset:37888
	ds_read_b128 v[200:203], v242 offset:38912
	ds_read_b128 v[204:207], v242 offset:39936
	buffer_load_dwordx4 v178, s[76:79], s63 offen lds
	s_mov_b32 m0, s23
	s_nop 0
	buffer_load_dwordx4 v237, s[76:79], s63 offen lds
	s_waitcnt vmcnt(8)
	s_waitcnt lgkmcnt(0)
	s_setprio 1
	s_barrier
	v_mfma_f32_16x16x32_bf16 v[130:133], v[134:137], v[166:169], v[130:133]
	v_mfma_f32_16x16x32_bf16 v[130:133], v[138:141], v[170:173], v[130:133]
	v_mfma_f32_16x16x32_bf16 v[126:129], v[142:145], v[166:169], v[126:129]
	v_mfma_f32_16x16x32_bf16 v[126:129], v[146:149], v[170:173], v[126:129]
	v_mfma_f32_16x16x32_bf16 v[118:121], v[142:145], v[184:187], v[118:121]
	v_mfma_f32_16x16x32_bf16 v[118:121], v[146:149], v[188:191], v[118:121]
	v_mfma_f32_16x16x32_bf16 v[122:125], v[134:137], v[184:187], v[122:125]
	v_mfma_f32_16x16x32_bf16 v[122:125], v[138:141], v[188:191], v[122:125]
	v_mfma_f32_16x16x32_bf16 v[114:117], v[134:137], v[192:195], v[114:117]
	v_mfma_f32_16x16x32_bf16 v[114:117], v[138:141], v[196:199], v[114:117]
	v_mfma_f32_16x16x32_bf16 v[110:113], v[142:145], v[192:195], v[110:113]
	v_mfma_f32_16x16x32_bf16 v[110:113], v[146:149], v[196:199], v[110:113]
	v_mfma_f32_16x16x32_bf16 v[102:105], v[142:145], v[200:203], v[102:105]
	v_mfma_f32_16x16x32_bf16 v[102:105], v[146:149], v[204:207], v[102:105]
	v_mfma_f32_16x16x32_bf16 v[106:109], v[134:137], v[200:203], v[106:109]
	v_mfma_f32_16x16x32_bf16 v[106:109], v[138:141], v[204:207], v[106:109]
	v_mfma_f32_16x16x32_bf16 v[62:65], v[150:153], v[166:169], v[62:65]
	v_mfma_f32_16x16x32_bf16 v[62:65], v[154:157], v[170:173], v[62:65]
	v_mfma_f32_16x16x32_bf16 v[58:61], v[158:161], v[166:169], v[58:61]
	v_mfma_f32_16x16x32_bf16 v[58:61], v[162:165], v[170:173], v[58:61]
	v_mfma_f32_16x16x32_bf16 v[50:53], v[158:161], v[184:187], v[50:53]
	v_mfma_f32_16x16x32_bf16 v[50:53], v[162:165], v[188:191], v[50:53]
	v_mfma_f32_16x16x32_bf16 v[54:57], v[150:153], v[184:187], v[54:57]
	v_mfma_f32_16x16x32_bf16 v[54:57], v[154:157], v[188:191], v[54:57]
	v_mfma_f32_16x16x32_bf16 v[46:49], v[150:153], v[192:195], v[46:49]
	v_mfma_f32_16x16x32_bf16 v[46:49], v[154:157], v[196:199], v[46:49]
	v_mfma_f32_16x16x32_bf16 v[42:45], v[158:161], v[192:195], v[42:45]
	v_mfma_f32_16x16x32_bf16 v[42:45], v[162:165], v[196:199], v[42:45]
	v_mfma_f32_16x16x32_bf16 v[34:37], v[158:161], v[200:203], v[34:37]
	v_mfma_f32_16x16x32_bf16 v[34:37], v[162:165], v[204:207], v[34:37]
	v_mfma_f32_16x16x32_bf16 v[38:41], v[150:153], v[200:203], v[38:41]
	v_mfma_f32_16x16x32_bf16 v[38:41], v[154:157], v[204:207], v[38:41]
	s_barrier
	s_setprio 0
	s_mov_b32 m0, s54
	s_or_b32 s63, s62, 0x80
	ds_read_b128 v[166:169], v242 offset:49152
	ds_read_b128 v[170:173], v242 offset:50176
	ds_read_b128 v[184:187], v242 offset:51200
	ds_read_b128 v[188:191], v242 offset:52224
	ds_read_b128 v[192:195], v242 offset:53248
	ds_read_b128 v[196:199], v242 offset:54272
	ds_read_b128 v[200:203], v242 offset:55296
	ds_read_b128 v[204:207], v242 offset:56320
	buffer_load_dwordx4 v179, s[44:47], s63 offen lds
	s_mov_b32 m0, s55
	s_add_i32 s62, s62, 0x158080
	buffer_load_dwordx4 v238, s[44:47], s63 offen lds
	s_mov_b32 m0, s70
	s_nop 0
	buffer_load_dwordx4 v179, s[44:47], s62 offen lds
	s_mov_b32 m0, s71
	s_nop 0
	buffer_load_dwordx4 v238, s[44:47], s62 offen lds
	s_mov_b32 m0, s68
	s_cmpk_eq_i32 s60, 0x52
	buffer_load_dwordx4 v178, s[76:79], s61 offen lds
	s_mov_b32 m0, s69
	s_cselect_b64 vcc, s[48:49], 0
	buffer_load_dwordx4 v237, s[76:79], s61 offen lds
	s_waitcnt vmcnt(8)
	s_waitcnt lgkmcnt(0)
	s_setprio 1
	s_barrier
	v_mfma_f32_16x16x32_bf16 v[98:101], v[134:137], v[166:169], v[98:101]
	v_mfma_f32_16x16x32_bf16 v[94:97], v[142:145], v[166:169], v[94:97]
	v_mfma_f32_16x16x32_bf16 v[90:93], v[134:137], v[184:187], v[90:93]
	v_mfma_f32_16x16x32_bf16 v[86:89], v[142:145], v[184:187], v[86:89]
	v_mfma_f32_16x16x32_bf16 v[80:83], v[134:137], v[192:195], v[82:85]
	v_mfma_f32_16x16x32_bf16 v[74:77], v[142:145], v[192:195], v[76:79]
	v_mfma_f32_16x16x32_bf16 v[70:73], v[134:137], v[200:203], v[70:73]
	v_mfma_f32_16x16x32_bf16 v[66:69], v[142:145], v[200:203], v[66:69]
	v_mfma_f32_16x16x32_bf16 v[98:101], v[138:141], v[170:173], v[98:101]
	v_mfma_f32_16x16x32_bf16 v[94:97], v[146:149], v[170:173], v[94:97]
	v_mfma_f32_16x16x32_bf16 v[90:93], v[138:141], v[188:191], v[90:93]
	v_mfma_f32_16x16x32_bf16 v[86:89], v[146:149], v[188:191], v[86:89]
	v_mfma_f32_16x16x32_bf16 v[82:85], v[138:141], v[196:199], v[80:83]
	v_mfma_f32_16x16x32_bf16 v[78:81], v[146:149], v[196:199], v[74:77]
	v_mfma_f32_16x16x32_bf16 v[72:75], v[138:141], v[204:207], v[70:73]
	v_mfma_f32_16x16x32_bf16 v[66:69], v[146:149], v[204:207], v[66:69]
	v_mfma_f32_16x16x32_bf16 v[30:33], v[150:153], v[166:169], v[30:33]
	v_mfma_f32_16x16x32_bf16 v[26:29], v[158:161], v[166:169], v[26:29]
	v_mfma_f32_16x16x32_bf16 v[22:25], v[150:153], v[184:187], v[22:25]
	v_mfma_f32_16x16x32_bf16 v[18:21], v[158:161], v[184:187], v[18:21]
	v_mfma_f32_16x16x32_bf16 v[14:17], v[150:153], v[192:195], v[14:17]
	v_mfma_f32_16x16x32_bf16 v[10:13], v[158:161], v[192:195], v[10:13]
	v_mfma_f32_16x16x32_bf16 v[6:9], v[150:153], v[200:203], v[6:9]
	v_mfma_f32_16x16x32_bf16 v[2:5], v[158:161], v[200:203], v[2:5]
	v_mfma_f32_16x16x32_bf16 v[30:33], v[154:157], v[170:173], v[30:33]
	v_mfma_f32_16x16x32_bf16 v[26:29], v[162:165], v[170:173], v[26:29]
	v_mfma_f32_16x16x32_bf16 v[22:25], v[154:157], v[188:191], v[22:25]
	v_mfma_f32_16x16x32_bf16 v[18:21], v[162:165], v[188:191], v[18:21]
	v_mfma_f32_16x16x32_bf16 v[14:17], v[154:157], v[196:199], v[14:17]
	v_mfma_f32_16x16x32_bf16 v[10:13], v[162:165], v[196:199], v[10:13]
	v_mfma_f32_16x16x32_bf16 v[6:9], v[154:157], v[204:207], v[6:9]
	v_mfma_f32_16x16x32_bf16 v[2:5], v[162:165], v[204:207], v[2:5]
	s_cbranch_vccnz .Lee_skip_1750
	s_barrier
.Lee_skip_1750:
	s_setprio 0
	s_add_i32 s60, s60, 2
	s_addk_i32 s40, 0x100
	s_addk_i32 s41, 0x100
	s_cmpk_gt_u32 s60, 0x53
	s_cbranch_scc0 .LBB0_1750
